# GEMM1 a_v epilogue: canonicalising v_max x,x,x removed (128), gelu*g multiplies packed (64)
# baseline (speedup 1.0000x reference)
.LBB0_280:
	s_andn2_b64 vcc, exec, s[70:71]
	s_cbranch_vccnz .LBB0_314
	v_ashrrev_i32_e32 v155, 31, v154
	v_lshl_add_u64 v[150:151], v[154:155], 2, s[14:15]
	global_load_dword v169, v[150:151], off
	v_lshlrev_b64 v[146:147], 15, v[154:155]
	v_lshl_add_u64 v[146:147], s[22:23], 0, v[146:147]
	v_and_b32_e32 v157, 0x7fffffff, v125
	v_and_b32_e32 v156, 0x7fffffff, v124
	v_lshl_add_u64 v[148:149], v[146:147], 0, v[152:153]
	v_pk_fma_f32 v[146:147], v[156:157], s[38:39], 1.0 op_sel_hi:[1,0,0]
	v_pk_mul_f32 v[174:175], v[124:125], v[124:125]
	v_rcp_f32_e32 v158, v146
	v_rcp_f32_e32 v159, v147
	v_mov_b64_e32 v[146:147], s[42:43]
	v_and_b32_e32 v171, 0x7fffffff, v127
	v_and_b32_e32 v170, 0x7fffffff, v126
	v_pk_fma_f32 v[172:173], v[158:159], s[40:41], v[146:147] op_sel_hi:[1,0,0]
	v_pk_mul_f32 v[174:175], v[174:175], s[50:51] op_sel_hi:[1,0]
	v_pk_fma_f32 v[172:173], v[158:159], v[172:173], s[44:45] op_sel_hi:[1,1,0]
	v_exp_f32_e32 v174, v174
	v_exp_f32_e32 v175, v175
	v_pk_fma_f32 v[176:177], v[170:171], s[38:39], 1.0 op_sel_hi:[1,0,0]
	v_pk_fma_f32 v[172:173], v[158:159], v[172:173], s[46:47] op_sel_hi:[1,1,0]
	v_rcp_f32_e32 v176, v176
	v_rcp_f32_e32 v177, v177
	v_pk_fma_f32 v[172:173], v[158:159], v[172:173], s[48:49] op_sel_hi:[1,1,0]
	v_pk_mul_f32 v[158:159], v[158:159], v[172:173]
	v_pk_mul_f32 v[172:173], v[126:127], v[126:127]
	v_max_f32_e32 v124, 0, v124
	v_max_f32_e32 v125, 0, v125
	v_pk_mul_f32 v[158:159], v[174:175], v[158:159]
	v_pk_fma_f32 v[156:157], v[156:157], v[158:159], v[124:125] neg_lo:[1,0,0] neg_hi:[1,0,0]
	v_pk_fma_f32 v[124:125], v[176:177], s[40:41], v[146:147] op_sel_hi:[1,0,0]
	v_pk_mul_f32 v[158:159], v[172:173], s[50:51] op_sel_hi:[1,0]
	v_pk_fma_f32 v[124:125], v[176:177], v[124:125], s[44:45] op_sel_hi:[1,1,0]
	v_exp_f32_e32 v158, v158
	v_exp_f32_e32 v159, v159
	v_pk_fma_f32 v[124:125], v[176:177], v[124:125], s[46:47] op_sel_hi:[1,1,0]
	v_pk_fma_f32 v[124:125], v[176:177], v[124:125], s[48:49] op_sel_hi:[1,1,0]
	v_max_f32_e32 v126, 0, v126
	v_pk_mul_f32 v[124:125], v[176:177], v[124:125]
	v_max_f32_e32 v127, 0, v127
	v_pk_mul_f32 v[124:125], v[158:159], v[124:125]
	v_and_b32_e32 v159, 0x7fffffff, v121
	v_and_b32_e32 v158, 0x7fffffff, v120
	v_pk_fma_f32 v[172:173], v[158:159], s[38:39], 1.0 op_sel_hi:[1,0,0]
	v_pk_mul_f32 v[174:175], v[120:121], v[120:121]
	v_rcp_f32_e32 v172, v172
	v_rcp_f32_e32 v173, v173
	v_pk_fma_f32 v[126:127], v[170:171], v[124:125], v[126:127] neg_lo:[1,0,0] neg_hi:[1,0,0]
	v_and_b32_e32 v171, 0x7fffffff, v123
	v_and_b32_e32 v170, 0x7fffffff, v122
	v_pk_fma_f32 v[124:125], v[172:173], s[40:41], v[146:147] op_sel_hi:[1,0,0]
	v_pk_mul_f32 v[174:175], v[174:175], s[50:51] op_sel_hi:[1,0]
	v_pk_fma_f32 v[124:125], v[172:173], v[124:125], s[44:45] op_sel_hi:[1,1,0]
	v_exp_f32_e32 v174, v174
	v_exp_f32_e32 v175, v175
	v_pk_fma_f32 v[176:177], v[170:171], s[38:39], 1.0 op_sel_hi:[1,0,0]
	v_pk_fma_f32 v[124:125], v[172:173], v[124:125], s[46:47] op_sel_hi:[1,1,0]
	v_rcp_f32_e32 v176, v176
	v_rcp_f32_e32 v177, v177
	v_pk_fma_f32 v[124:125], v[172:173], v[124:125], s[48:49] op_sel_hi:[1,1,0]
	v_pk_mul_f32 v[124:125], v[172:173], v[124:125]
	v_pk_mul_f32 v[172:173], v[122:123], v[122:123]
	v_max_f32_e32 v120, 0, v120
	v_max_f32_e32 v121, 0, v121
	v_pk_mul_f32 v[124:125], v[174:175], v[124:125]
	v_pk_fma_f32 v[124:125], v[158:159], v[124:125], v[120:121] neg_lo:[1,0,0] neg_hi:[1,0,0]
	v_pk_fma_f32 v[120:121], v[176:177], s[40:41], v[146:147] op_sel_hi:[1,0,0]
	v_pk_mul_f32 v[158:159], v[172:173], s[50:51] op_sel_hi:[1,0]
	v_pk_fma_f32 v[120:121], v[176:177], v[120:121], s[44:45] op_sel_hi:[1,1,0]
	v_exp_f32_e32 v158, v158
	v_exp_f32_e32 v159, v159
	v_pk_fma_f32 v[120:121], v[176:177], v[120:121], s[46:47] op_sel_hi:[1,1,0]
	v_pk_fma_f32 v[120:121], v[176:177], v[120:121], s[48:49] op_sel_hi:[1,1,0]
	v_max_f32_e32 v122, 0, v122
	v_pk_mul_f32 v[120:121], v[176:177], v[120:121]
	v_max_f32_e32 v123, 0, v123
	v_pk_mul_f32 v[120:121], v[158:159], v[120:121]
	v_pk_mul_f32 v[174:175], v[116:117], v[116:117]
	v_pk_fma_f32 v[122:123], v[170:171], v[120:121], v[122:123] neg_lo:[1,0,0] neg_hi:[1,0,0]
	s_waitcnt vmcnt(0)
	v_pk_mul_f32 v[120:121], v[156:157], v[168:169] op_sel:[0,1] op_sel_hi:[1,1]
	v_cvt_pk_bf16_f32 v170, v120, v121
	v_pk_mul_f32 v[120:121], v[126:127], v[168:169] op_sel:[0,1] op_sel_hi:[1,1]
	v_cvt_pk_bf16_f32 v171, v120, v121
	v_pk_mul_f32 v[120:121], v[124:125], v[168:169] op_sel:[0,1] op_sel_hi:[1,1]
	v_cvt_pk_bf16_f32 v172, v120, v121
	v_pk_mul_f32 v[120:121], v[122:123], v[168:169] op_sel:[0,1] op_sel_hi:[1,1]
	v_cvt_pk_bf16_f32 v173, v120, v121
	v_and_b32_e32 v121, 0x7fffffff, v117
	v_and_b32_e32 v120, 0x7fffffff, v116
	v_pk_fma_f32 v[158:159], v[120:121], s[38:39], 1.0 op_sel_hi:[1,0,0]
	global_store_dwordx4 v[148:149], v[170:173], off
	v_rcp_f32_e32 v158, v158
	v_rcp_f32_e32 v159, v159
	v_and_b32_e32 v171, 0x7fffffff, v119
	v_and_b32_e32 v170, 0x7fffffff, v118
	v_pk_mul_f32 v[174:175], v[174:175], s[50:51] op_sel_hi:[1,0]
	v_pk_fma_f32 v[172:173], v[158:159], s[40:41], v[146:147] op_sel_hi:[1,0,0]
	v_exp_f32_e32 v174, v174
	v_pk_fma_f32 v[172:173], v[158:159], v[172:173], s[44:45] op_sel_hi:[1,1,0]
	v_exp_f32_e32 v175, v175
	v_pk_fma_f32 v[176:177], v[170:171], s[38:39], 1.0 op_sel_hi:[1,0,0]
	v_pk_fma_f32 v[172:173], v[158:159], v[172:173], s[46:47] op_sel_hi:[1,1,0]
	v_rcp_f32_e32 v176, v176
	v_rcp_f32_e32 v177, v177
	v_pk_fma_f32 v[172:173], v[158:159], v[172:173], s[48:49] op_sel_hi:[1,1,0]
	v_pk_mul_f32 v[158:159], v[158:159], v[172:173]
	v_pk_mul_f32 v[172:173], v[118:119], v[118:119]
	v_max_f32_e32 v116, 0, v116
	v_max_f32_e32 v117, 0, v117
	v_pk_mul_f32 v[158:159], v[174:175], v[158:159]
	v_pk_fma_f32 v[120:121], v[120:121], v[158:159], v[116:117] neg_lo:[1,0,0] neg_hi:[1,0,0]
	v_pk_fma_f32 v[116:117], v[176:177], s[40:41], v[146:147] op_sel_hi:[1,0,0]
	v_pk_mul_f32 v[158:159], v[172:173], s[50:51] op_sel_hi:[1,0]
	v_pk_fma_f32 v[116:117], v[176:177], v[116:117], s[44:45] op_sel_hi:[1,1,0]
	v_exp_f32_e32 v158, v158
	v_exp_f32_e32 v159, v159
	v_pk_fma_f32 v[116:117], v[176:177], v[116:117], s[46:47] op_sel_hi:[1,1,0]
	v_pk_fma_f32 v[116:117], v[176:177], v[116:117], s[48:49] op_sel_hi:[1,1,0]
	v_max_f32_e32 v118, 0, v118
	v_pk_mul_f32 v[116:117], v[176:177], v[116:117]
	v_max_f32_e32 v119, 0, v119
	v_pk_mul_f32 v[116:117], v[158:159], v[116:117]
	v_and_b32_e32 v159, 0x7fffffff, v113
	v_and_b32_e32 v158, 0x7fffffff, v112
	v_pk_fma_f32 v[172:173], v[158:159], s[38:39], 1.0 op_sel_hi:[1,0,0]
	v_pk_mul_f32 v[174:175], v[112:113], v[112:113]
	v_rcp_f32_e32 v172, v172
	v_rcp_f32_e32 v173, v173
	v_pk_fma_f32 v[118:119], v[170:171], v[116:117], v[118:119] neg_lo:[1,0,0] neg_hi:[1,0,0]
	v_and_b32_e32 v171, 0x7fffffff, v115
	v_and_b32_e32 v170, 0x7fffffff, v114
	v_pk_fma_f32 v[116:117], v[172:173], s[40:41], v[146:147] op_sel_hi:[1,0,0]
	v_pk_mul_f32 v[174:175], v[174:175], s[50:51] op_sel_hi:[1,0]
	v_pk_fma_f32 v[116:117], v[172:173], v[116:117], s[44:45] op_sel_hi:[1,1,0]
	v_exp_f32_e32 v174, v174
	v_exp_f32_e32 v175, v175
	v_pk_fma_f32 v[176:177], v[170:171], s[38:39], 1.0 op_sel_hi:[1,0,0]
	v_pk_fma_f32 v[116:117], v[172:173], v[116:117], s[46:47] op_sel_hi:[1,1,0]
	v_rcp_f32_e32 v176, v176
	v_rcp_f32_e32 v177, v177
	v_pk_fma_f32 v[116:117], v[172:173], v[116:117], s[48:49] op_sel_hi:[1,1,0]
	v_pk_mul_f32 v[116:117], v[172:173], v[116:117]
	v_pk_mul_f32 v[172:173], v[114:115], v[114:115]
	v_max_f32_e32 v112, 0, v112
	v_max_f32_e32 v113, 0, v113
	v_pk_mul_f32 v[116:117], v[174:175], v[116:117]
	v_pk_fma_f32 v[116:117], v[158:159], v[116:117], v[112:113] neg_lo:[1,0,0] neg_hi:[1,0,0]
	v_pk_fma_f32 v[112:113], v[176:177], s[40:41], v[146:147] op_sel_hi:[1,0,0]
	v_pk_mul_f32 v[158:159], v[172:173], s[50:51] op_sel_hi:[1,0]
	v_pk_fma_f32 v[112:113], v[176:177], v[112:113], s[44:45] op_sel_hi:[1,1,0]
	v_exp_f32_e32 v158, v158
	v_exp_f32_e32 v159, v159
	v_pk_fma_f32 v[112:113], v[176:177], v[112:113], s[46:47] op_sel_hi:[1,1,0]
	v_pk_fma_f32 v[112:113], v[176:177], v[112:113], s[48:49] op_sel_hi:[1,1,0]
	v_max_f32_e32 v114, 0, v114
	v_pk_mul_f32 v[112:113], v[176:177], v[112:113]
	v_max_f32_e32 v115, 0, v115
	v_pk_mul_f32 v[112:113], v[158:159], v[112:113]
	v_pk_mul_f32 v[176:177], v[108:109], v[108:109]
	v_pk_fma_f32 v[112:113], v[170:171], v[112:113], v[114:115] neg_lo:[1,0,0] neg_hi:[1,0,0]
	v_pk_mul_f32 v[114:115], v[120:121], v[168:169] op_sel:[0,1] op_sel_hi:[1,1]
	v_cvt_pk_bf16_f32 v170, v114, v115
	v_pk_mul_f32 v[114:115], v[118:119], v[168:169] op_sel:[0,1] op_sel_hi:[1,1]
	v_cvt_pk_bf16_f32 v171, v114, v115
	v_pk_mul_f32 v[114:115], v[116:117], v[168:169] op_sel:[0,1] op_sel_hi:[1,1]
	v_cvt_pk_bf16_f32 v172, v114, v115
	v_pk_mul_f32 v[114:115], v[112:113], v[168:169] op_sel:[0,1] op_sel_hi:[1,1]
	v_cvt_pk_bf16_f32 v173, v114, v115
	global_store_dwordx4 v[148:149], v[170:173], off offset:256
	global_load_dword v155, v[150:151], off offset:64
	v_or_b32_e32 v114, 16, v154
	v_and_b32_e32 v171, 0x7fffffff, v109
	v_and_b32_e32 v170, 0x7fffffff, v108
	v_pk_fma_f32 v[158:159], v[170:171], s[38:39], 1.0 op_sel_hi:[1,0,0]
	v_ashrrev_i32_e32 v115, 31, v114
	v_rcp_f32_e32 v172, v158
	v_rcp_f32_e32 v173, v159
	v_lshlrev_b64 v[114:115], 15, v[114:115]
	v_lshl_add_u64 v[114:115], s[22:23], 0, v[114:115]
	v_lshl_add_u64 v[158:159], v[114:115], 0, v[152:153]
	v_and_b32_e32 v115, 0x7fffffff, v111
	v_and_b32_e32 v114, 0x7fffffff, v110
	v_pk_fma_f32 v[174:175], v[172:173], s[40:41], v[146:147] op_sel_hi:[1,0,0]
	v_pk_mul_f32 v[176:177], v[176:177], s[50:51] op_sel_hi:[1,0]
	v_pk_fma_f32 v[174:175], v[172:173], v[174:175], s[44:45] op_sel_hi:[1,1,0]
	v_exp_f32_e32 v176, v176
	v_exp_f32_e32 v177, v177
	v_pk_fma_f32 v[178:179], v[114:115], s[38:39], 1.0 op_sel_hi:[1,0,0]
	v_pk_fma_f32 v[174:175], v[172:173], v[174:175], s[46:47] op_sel_hi:[1,1,0]
	v_rcp_f32_e32 v178, v178
	v_rcp_f32_e32 v179, v179
	v_pk_fma_f32 v[174:175], v[172:173], v[174:175], s[48:49] op_sel_hi:[1,1,0]
	v_pk_mul_f32 v[172:173], v[172:173], v[174:175]
	v_pk_mul_f32 v[174:175], v[110:111], v[110:111]
	v_max_f32_e32 v108, 0, v108
	v_max_f32_e32 v109, 0, v109
	v_pk_mul_f32 v[172:173], v[176:177], v[172:173]
	v_pk_fma_f32 v[170:171], v[170:171], v[172:173], v[108:109] neg_lo:[1,0,0] neg_hi:[1,0,0]
	v_pk_fma_f32 v[108:109], v[178:179], s[40:41], v[146:147] op_sel_hi:[1,0,0]
	v_pk_mul_f32 v[172:173], v[174:175], s[50:51] op_sel_hi:[1,0]
	v_pk_fma_f32 v[108:109], v[178:179], v[108:109], s[44:45] op_sel_hi:[1,1,0]
	v_exp_f32_e32 v172, v172
	v_exp_f32_e32 v173, v173
	v_pk_fma_f32 v[108:109], v[178:179], v[108:109], s[46:47] op_sel_hi:[1,1,0]
	v_pk_fma_f32 v[108:109], v[178:179], v[108:109], s[48:49] op_sel_hi:[1,1,0]
	v_max_f32_e32 v110, 0, v110
	v_pk_mul_f32 v[108:109], v[178:179], v[108:109]
	v_max_f32_e32 v111, 0, v111
	v_pk_mul_f32 v[108:109], v[172:173], v[108:109]
	v_and_b32_e32 v173, 0x7fffffff, v105
	v_and_b32_e32 v172, 0x7fffffff, v104
	v_pk_fma_f32 v[174:175], v[172:173], s[38:39], 1.0 op_sel_hi:[1,0,0]
	v_pk_mul_f32 v[176:177], v[104:105], v[104:105]
	v_rcp_f32_e32 v174, v174
	v_rcp_f32_e32 v175, v175
	v_pk_fma_f32 v[110:111], v[114:115], v[108:109], v[110:111] neg_lo:[1,0,0] neg_hi:[1,0,0]
	v_and_b32_e32 v115, 0x7fffffff, v107
	v_and_b32_e32 v114, 0x7fffffff, v106
	v_pk_fma_f32 v[108:109], v[174:175], s[40:41], v[146:147] op_sel_hi:[1,0,0]
	v_pk_mul_f32 v[176:177], v[176:177], s[50:51] op_sel_hi:[1,0]
	v_pk_fma_f32 v[108:109], v[174:175], v[108:109], s[44:45] op_sel_hi:[1,1,0]
	v_exp_f32_e32 v176, v176
	v_exp_f32_e32 v177, v177
	v_pk_fma_f32 v[178:179], v[114:115], s[38:39], 1.0 op_sel_hi:[1,0,0]
	v_pk_fma_f32 v[108:109], v[174:175], v[108:109], s[46:47] op_sel_hi:[1,1,0]
	v_rcp_f32_e32 v178, v178
	v_rcp_f32_e32 v179, v179
	v_pk_fma_f32 v[108:109], v[174:175], v[108:109], s[48:49] op_sel_hi:[1,1,0]
	v_pk_mul_f32 v[108:109], v[174:175], v[108:109]
	v_pk_mul_f32 v[174:175], v[106:107], v[106:107]
	v_max_f32_e32 v104, 0, v104
	v_max_f32_e32 v105, 0, v105
	v_pk_mul_f32 v[108:109], v[176:177], v[108:109]
	v_pk_fma_f32 v[108:109], v[172:173], v[108:109], v[104:105] neg_lo:[1,0,0] neg_hi:[1,0,0]
	v_pk_fma_f32 v[104:105], v[178:179], s[40:41], v[146:147] op_sel_hi:[1,0,0]
	v_pk_mul_f32 v[172:173], v[174:175], s[50:51] op_sel_hi:[1,0]
	v_pk_fma_f32 v[104:105], v[178:179], v[104:105], s[44:45] op_sel_hi:[1,1,0]
	v_exp_f32_e32 v172, v172
	v_exp_f32_e32 v173, v173
	v_pk_fma_f32 v[104:105], v[178:179], v[104:105], s[46:47] op_sel_hi:[1,1,0]
	v_pk_fma_f32 v[104:105], v[178:179], v[104:105], s[48:49] op_sel_hi:[1,1,0]
	v_max_f32_e32 v106, 0, v106
	v_pk_mul_f32 v[104:105], v[178:179], v[104:105]
	v_max_f32_e32 v107, 0, v107
	v_pk_mul_f32 v[104:105], v[172:173], v[104:105]
	v_pk_mul_f32 v[174:175], v[100:101], v[100:101]
	v_pk_fma_f32 v[104:105], v[114:115], v[104:105], v[106:107] neg_lo:[1,0,0] neg_hi:[1,0,0]
	v_pk_mul_f32 v[106:107], v[170:171], v[170:171]
	v_pk_mul_f32 v[174:175], v[174:175], s[50:51] op_sel_hi:[1,0]
	v_pk_fma_f32 v[114:115], v[156:157], v[156:157], v[106:107]
	s_waitcnt vmcnt(0)
	v_pk_mul_f32 v[106:107], v[170:171], v[154:155] op_sel:[0,1] op_sel_hi:[1,1]
	v_cvt_pk_bf16_f32 v170, v106, v107
	v_pk_mul_f32 v[106:107], v[110:111], v[154:155] op_sel:[0,1] op_sel_hi:[1,1]
	v_cvt_pk_bf16_f32 v171, v106, v107
	v_pk_mul_f32 v[106:107], v[108:109], v[154:155] op_sel:[0,1] op_sel_hi:[1,1]
	v_cvt_pk_bf16_f32 v172, v106, v107
	v_pk_mul_f32 v[106:107], v[104:105], v[154:155] op_sel:[0,1] op_sel_hi:[1,1]
	v_cvt_pk_bf16_f32 v173, v106, v107
	v_and_b32_e32 v107, 0x7fffffff, v101
	v_and_b32_e32 v106, 0x7fffffff, v100
	v_pk_fma_f32 v[156:157], v[106:107], s[38:39], 1.0 op_sel_hi:[1,0,0]
	global_store_dwordx4 v[158:159], v[170:173], off
	v_rcp_f32_e32 v156, v156
	v_rcp_f32_e32 v157, v157
	v_and_b32_e32 v171, 0x7fffffff, v103
	v_and_b32_e32 v170, 0x7fffffff, v102
	v_exp_f32_e32 v174, v174
	v_pk_fma_f32 v[172:173], v[156:157], s[40:41], v[146:147] op_sel_hi:[1,0,0]
	v_exp_f32_e32 v175, v175
	v_pk_fma_f32 v[172:173], v[156:157], v[172:173], s[44:45] op_sel_hi:[1,1,0]
	v_pk_fma_f32 v[176:177], v[170:171], s[38:39], 1.0 op_sel_hi:[1,0,0]
	v_pk_fma_f32 v[172:173], v[156:157], v[172:173], s[46:47] op_sel_hi:[1,1,0]
	v_rcp_f32_e32 v176, v176
	v_rcp_f32_e32 v177, v177
	v_pk_fma_f32 v[172:173], v[156:157], v[172:173], s[48:49] op_sel_hi:[1,1,0]
	v_pk_mul_f32 v[156:157], v[156:157], v[172:173]
	v_pk_mul_f32 v[172:173], v[102:103], v[102:103]
	v_max_f32_e32 v100, 0, v100
	v_max_f32_e32 v101, 0, v101
	v_pk_mul_f32 v[156:157], v[174:175], v[156:157]
	v_pk_fma_f32 v[106:107], v[106:107], v[156:157], v[100:101] neg_lo:[1,0,0] neg_hi:[1,0,0]
	v_pk_fma_f32 v[100:101], v[176:177], s[40:41], v[146:147] op_sel_hi:[1,0,0]
	v_pk_mul_f32 v[156:157], v[172:173], s[50:51] op_sel_hi:[1,0]
	v_pk_fma_f32 v[100:101], v[176:177], v[100:101], s[44:45] op_sel_hi:[1,1,0]
	v_exp_f32_e32 v156, v156
	v_exp_f32_e32 v157, v157
	v_pk_fma_f32 v[100:101], v[176:177], v[100:101], s[46:47] op_sel_hi:[1,1,0]
	v_pk_fma_f32 v[100:101], v[176:177], v[100:101], s[48:49] op_sel_hi:[1,1,0]
	v_max_f32_e32 v102, 0, v102
	v_pk_mul_f32 v[100:101], v[176:177], v[100:101]
	v_max_f32_e32 v103, 0, v103
	v_pk_mul_f32 v[100:101], v[156:157], v[100:101]
	v_and_b32_e32 v157, 0x7fffffff, v97
	v_and_b32_e32 v156, 0x7fffffff, v96
	v_pk_fma_f32 v[172:173], v[156:157], s[38:39], 1.0 op_sel_hi:[1,0,0]
	v_pk_mul_f32 v[174:175], v[96:97], v[96:97]
	v_rcp_f32_e32 v172, v172
	v_rcp_f32_e32 v173, v173
	v_pk_fma_f32 v[102:103], v[170:171], v[100:101], v[102:103] neg_lo:[1,0,0] neg_hi:[1,0,0]
	v_and_b32_e32 v171, 0x7fffffff, v99
	v_and_b32_e32 v170, 0x7fffffff, v98
	v_pk_fma_f32 v[100:101], v[172:173], s[40:41], v[146:147] op_sel_hi:[1,0,0]
	v_pk_mul_f32 v[174:175], v[174:175], s[50:51] op_sel_hi:[1,0]
	v_pk_fma_f32 v[100:101], v[172:173], v[100:101], s[44:45] op_sel_hi:[1,1,0]
	v_exp_f32_e32 v174, v174
	v_exp_f32_e32 v175, v175
	v_pk_fma_f32 v[176:177], v[170:171], s[38:39], 1.0 op_sel_hi:[1,0,0]
	v_pk_fma_f32 v[100:101], v[172:173], v[100:101], s[46:47] op_sel_hi:[1,1,0]
	v_rcp_f32_e32 v176, v176
	v_rcp_f32_e32 v177, v177
	v_pk_fma_f32 v[100:101], v[172:173], v[100:101], s[48:49] op_sel_hi:[1,1,0]
	v_pk_mul_f32 v[100:101], v[172:173], v[100:101]
	v_pk_mul_f32 v[172:173], v[98:99], v[98:99]
	v_max_f32_e32 v96, 0, v96
	v_max_f32_e32 v97, 0, v97
	v_pk_mul_f32 v[100:101], v[174:175], v[100:101]
	v_pk_fma_f32 v[100:101], v[156:157], v[100:101], v[96:97] neg_lo:[1,0,0] neg_hi:[1,0,0]
	v_pk_fma_f32 v[96:97], v[176:177], s[40:41], v[146:147] op_sel_hi:[1,0,0]
	v_pk_mul_f32 v[156:157], v[172:173], s[50:51] op_sel_hi:[1,0]
	v_pk_fma_f32 v[96:97], v[176:177], v[96:97], s[44:45] op_sel_hi:[1,1,0]
	v_exp_f32_e32 v156, v156
	v_exp_f32_e32 v157, v157
	v_pk_fma_f32 v[96:97], v[176:177], v[96:97], s[46:47] op_sel_hi:[1,1,0]
	v_pk_fma_f32 v[96:97], v[176:177], v[96:97], s[48:49] op_sel_hi:[1,1,0]
	v_max_f32_e32 v98, 0, v98
	v_pk_mul_f32 v[96:97], v[176:177], v[96:97]
	v_max_f32_e32 v99, 0, v99
	v_pk_mul_f32 v[96:97], v[156:157], v[96:97]
	v_pk_mul_f32 v[174:175], v[92:93], v[92:93]
	v_pk_fma_f32 v[96:97], v[170:171], v[96:97], v[98:99] neg_lo:[1,0,0] neg_hi:[1,0,0]
	v_pk_mul_f32 v[98:99], v[106:107], v[154:155] op_sel:[0,1] op_sel_hi:[1,1]
	v_cvt_pk_bf16_f32 v170, v98, v99
	v_pk_mul_f32 v[98:99], v[102:103], v[154:155] op_sel:[0,1] op_sel_hi:[1,1]
	v_cvt_pk_bf16_f32 v171, v98, v99
	v_pk_mul_f32 v[98:99], v[100:101], v[154:155] op_sel:[0,1] op_sel_hi:[1,1]
	v_cvt_pk_bf16_f32 v172, v98, v99
	v_pk_mul_f32 v[98:99], v[96:97], v[154:155] op_sel:[0,1] op_sel_hi:[1,1]
	v_cvt_pk_bf16_f32 v173, v98, v99
	global_store_dwordx4 v[158:159], v[170:173], off offset:256
	global_load_dword v155, v[150:151], off offset:128
	v_and_b32_e32 v159, 0x7fffffff, v93
	v_and_b32_e32 v158, 0x7fffffff, v92
	v_pk_fma_f32 v[156:157], v[158:159], s[38:39], 1.0 op_sel_hi:[1,0,0]
	v_or_b32_e32 v98, 32, v154
	v_rcp_f32_e32 v170, v156
	v_rcp_f32_e32 v171, v157
	v_ashrrev_i32_e32 v99, 31, v98
	v_lshlrev_b64 v[98:99], 15, v[98:99]
	v_lshl_add_u64 v[98:99], s[22:23], 0, v[98:99]
	v_lshl_add_u64 v[156:157], v[98:99], 0, v[152:153]
	v_and_b32_e32 v99, 0x7fffffff, v95
	v_and_b32_e32 v98, 0x7fffffff, v94
	v_pk_fma_f32 v[172:173], v[170:171], s[40:41], v[146:147] op_sel_hi:[1,0,0]
	v_pk_mul_f32 v[174:175], v[174:175], s[50:51] op_sel_hi:[1,0]
	v_pk_fma_f32 v[172:173], v[170:171], v[172:173], s[44:45] op_sel_hi:[1,1,0]
	v_exp_f32_e32 v174, v174
	v_exp_f32_e32 v175, v175
	v_pk_fma_f32 v[176:177], v[98:99], s[38:39], 1.0 op_sel_hi:[1,0,0]
	v_pk_fma_f32 v[172:173], v[170:171], v[172:173], s[46:47] op_sel_hi:[1,1,0]
	v_rcp_f32_e32 v176, v176
	v_rcp_f32_e32 v177, v177
	v_pk_fma_f32 v[172:173], v[170:171], v[172:173], s[48:49] op_sel_hi:[1,1,0]
	v_pk_mul_f32 v[170:171], v[170:171], v[172:173]
	v_pk_mul_f32 v[172:173], v[94:95], v[94:95]
	v_max_f32_e32 v92, 0, v92
	v_max_f32_e32 v93, 0, v93
	v_pk_mul_f32 v[170:171], v[174:175], v[170:171]
	v_pk_fma_f32 v[158:159], v[158:159], v[170:171], v[92:93] neg_lo:[1,0,0] neg_hi:[1,0,0]
	v_pk_fma_f32 v[92:93], v[176:177], s[40:41], v[146:147] op_sel_hi:[1,0,0]
	v_pk_mul_f32 v[170:171], v[172:173], s[50:51] op_sel_hi:[1,0]
	v_pk_fma_f32 v[92:93], v[176:177], v[92:93], s[44:45] op_sel_hi:[1,1,0]
	v_exp_f32_e32 v170, v170
	v_exp_f32_e32 v171, v171
	v_pk_fma_f32 v[92:93], v[176:177], v[92:93], s[46:47] op_sel_hi:[1,1,0]
	v_pk_fma_f32 v[92:93], v[176:177], v[92:93], s[48:49] op_sel_hi:[1,1,0]
	v_max_f32_e32 v94, 0, v94
	v_pk_mul_f32 v[92:93], v[176:177], v[92:93]
	v_max_f32_e32 v95, 0, v95
	v_pk_mul_f32 v[92:93], v[170:171], v[92:93]
	v_and_b32_e32 v171, 0x7fffffff, v89
	v_and_b32_e32 v170, 0x7fffffff, v88
	v_pk_fma_f32 v[172:173], v[170:171], s[38:39], 1.0 op_sel_hi:[1,0,0]
	v_pk_mul_f32 v[174:175], v[88:89], v[88:89]
	v_rcp_f32_e32 v172, v172
	v_rcp_f32_e32 v173, v173
	v_pk_fma_f32 v[94:95], v[98:99], v[92:93], v[94:95] neg_lo:[1,0,0] neg_hi:[1,0,0]
	v_and_b32_e32 v99, 0x7fffffff, v91
	v_and_b32_e32 v98, 0x7fffffff, v90
	v_pk_fma_f32 v[92:93], v[172:173], s[40:41], v[146:147] op_sel_hi:[1,0,0]
	v_pk_mul_f32 v[174:175], v[174:175], s[50:51] op_sel_hi:[1,0]
	v_pk_fma_f32 v[92:93], v[172:173], v[92:93], s[44:45] op_sel_hi:[1,1,0]
	v_exp_f32_e32 v174, v174
	v_exp_f32_e32 v175, v175
	v_pk_fma_f32 v[176:177], v[98:99], s[38:39], 1.0 op_sel_hi:[1,0,0]
	v_pk_fma_f32 v[92:93], v[172:173], v[92:93], s[46:47] op_sel_hi:[1,1,0]
	v_rcp_f32_e32 v176, v176
	v_rcp_f32_e32 v177, v177
	v_pk_fma_f32 v[92:93], v[172:173], v[92:93], s[48:49] op_sel_hi:[1,1,0]
	v_pk_mul_f32 v[92:93], v[172:173], v[92:93]
	v_pk_mul_f32 v[172:173], v[90:91], v[90:91]
	v_max_f32_e32 v88, 0, v88
	v_max_f32_e32 v89, 0, v89
	v_pk_mul_f32 v[92:93], v[174:175], v[92:93]
	v_pk_fma_f32 v[92:93], v[170:171], v[92:93], v[88:89] neg_lo:[1,0,0] neg_hi:[1,0,0]
	v_pk_fma_f32 v[88:89], v[176:177], s[40:41], v[146:147] op_sel_hi:[1,0,0]
	v_pk_mul_f32 v[170:171], v[172:173], s[50:51] op_sel_hi:[1,0]
	v_pk_fma_f32 v[88:89], v[176:177], v[88:89], s[44:45] op_sel_hi:[1,1,0]
	v_exp_f32_e32 v170, v170
	v_exp_f32_e32 v171, v171
	v_pk_fma_f32 v[88:89], v[176:177], v[88:89], s[46:47] op_sel_hi:[1,1,0]
	v_pk_fma_f32 v[88:89], v[176:177], v[88:89], s[48:49] op_sel_hi:[1,1,0]
	v_max_f32_e32 v90, 0, v90
	v_pk_mul_f32 v[88:89], v[176:177], v[88:89]
	v_max_f32_e32 v91, 0, v91
	v_pk_mul_f32 v[88:89], v[170:171], v[88:89]
	s_nop 0
	v_pk_fma_f32 v[88:89], v[98:99], v[88:89], v[90:91] neg_lo:[1,0,0] neg_hi:[1,0,0]
	s_waitcnt vmcnt(0)
	v_pk_mul_f32 v[90:91], v[158:159], v[154:155] op_sel:[0,1] op_sel_hi:[1,1]
	v_cvt_pk_bf16_f32 v170, v90, v91
	v_pk_mul_f32 v[90:91], v[94:95], v[154:155] op_sel:[0,1] op_sel_hi:[1,1]
	v_cvt_pk_bf16_f32 v171, v90, v91
	v_pk_mul_f32 v[90:91], v[92:93], v[154:155] op_sel:[0,1] op_sel_hi:[1,1]
	v_cvt_pk_bf16_f32 v172, v90, v91
	v_pk_mul_f32 v[90:91], v[88:89], v[154:155] op_sel:[0,1] op_sel_hi:[1,1]
	v_cvt_pk_bf16_f32 v173, v90, v91
	v_and_b32_e32 v91, 0x7fffffff, v85
	v_and_b32_e32 v90, 0x7fffffff, v84
	v_pk_fma_f32 v[98:99], v[158:159], v[158:159], v[114:115]
	v_pk_fma_f32 v[114:115], v[90:91], s[38:39], 1.0 op_sel_hi:[1,0,0]
	global_store_dwordx4 v[156:157], v[170:173], off
	v_rcp_f32_e32 v114, v114
	v_rcp_f32_e32 v115, v115
	v_pk_mul_f32 v[172:173], v[84:85], v[84:85]
	v_and_b32_e32 v159, 0x7fffffff, v87
	v_and_b32_e32 v158, 0x7fffffff, v86
	v_pk_fma_f32 v[170:171], v[114:115], s[40:41], v[146:147] op_sel_hi:[1,0,0]
	v_pk_mul_f32 v[172:173], v[172:173], s[50:51] op_sel_hi:[1,0]
	v_pk_fma_f32 v[170:171], v[114:115], v[170:171], s[44:45] op_sel_hi:[1,1,0]
	v_exp_f32_e32 v172, v172
	v_exp_f32_e32 v173, v173
	v_pk_fma_f32 v[174:175], v[158:159], s[38:39], 1.0 op_sel_hi:[1,0,0]
	v_pk_fma_f32 v[170:171], v[114:115], v[170:171], s[46:47] op_sel_hi:[1,1,0]
	v_rcp_f32_e32 v174, v174
	v_rcp_f32_e32 v175, v175
	v_pk_fma_f32 v[170:171], v[114:115], v[170:171], s[48:49] op_sel_hi:[1,1,0]
	v_pk_mul_f32 v[114:115], v[114:115], v[170:171]
	v_pk_mul_f32 v[170:171], v[86:87], v[86:87]
	v_max_f32_e32 v84, 0, v84
	v_max_f32_e32 v85, 0, v85
	v_pk_mul_f32 v[114:115], v[172:173], v[114:115]
	v_pk_fma_f32 v[90:91], v[90:91], v[114:115], v[84:85] neg_lo:[1,0,0] neg_hi:[1,0,0]
	v_pk_fma_f32 v[84:85], v[174:175], s[40:41], v[146:147] op_sel_hi:[1,0,0]
	v_pk_mul_f32 v[114:115], v[170:171], s[50:51] op_sel_hi:[1,0]
	v_pk_fma_f32 v[84:85], v[174:175], v[84:85], s[44:45] op_sel_hi:[1,1,0]
	v_exp_f32_e32 v114, v114
	v_exp_f32_e32 v115, v115
	v_pk_fma_f32 v[84:85], v[174:175], v[84:85], s[46:47] op_sel_hi:[1,1,0]
	v_pk_fma_f32 v[84:85], v[174:175], v[84:85], s[48:49] op_sel_hi:[1,1,0]
	v_max_f32_e32 v86, 0, v86
	v_pk_mul_f32 v[84:85], v[174:175], v[84:85]
	v_max_f32_e32 v87, 0, v87
	v_pk_mul_f32 v[84:85], v[114:115], v[84:85]
	v_and_b32_e32 v115, 0x7fffffff, v81
	v_and_b32_e32 v114, 0x7fffffff, v80
	v_pk_fma_f32 v[170:171], v[114:115], s[38:39], 1.0 op_sel_hi:[1,0,0]
	v_pk_mul_f32 v[172:173], v[80:81], v[80:81]
	v_rcp_f32_e32 v170, v170
	v_rcp_f32_e32 v171, v171
	v_pk_fma_f32 v[86:87], v[158:159], v[84:85], v[86:87] neg_lo:[1,0,0] neg_hi:[1,0,0]
	v_and_b32_e32 v159, 0x7fffffff, v83
	v_and_b32_e32 v158, 0x7fffffff, v82
	v_pk_fma_f32 v[84:85], v[170:171], s[40:41], v[146:147] op_sel_hi:[1,0,0]
	v_pk_mul_f32 v[172:173], v[172:173], s[50:51] op_sel_hi:[1,0]
	v_pk_fma_f32 v[84:85], v[170:171], v[84:85], s[44:45] op_sel_hi:[1,1,0]
	v_exp_f32_e32 v172, v172
	v_exp_f32_e32 v173, v173
	v_pk_fma_f32 v[174:175], v[158:159], s[38:39], 1.0 op_sel_hi:[1,0,0]
	v_pk_fma_f32 v[84:85], v[170:171], v[84:85], s[46:47] op_sel_hi:[1,1,0]
	v_rcp_f32_e32 v174, v174
	v_rcp_f32_e32 v175, v175
	v_pk_fma_f32 v[84:85], v[170:171], v[84:85], s[48:49] op_sel_hi:[1,1,0]
	v_pk_mul_f32 v[84:85], v[170:171], v[84:85]
	v_pk_mul_f32 v[170:171], v[82:83], v[82:83]
	v_max_f32_e32 v80, 0, v80
	v_max_f32_e32 v81, 0, v81
	v_pk_mul_f32 v[84:85], v[172:173], v[84:85]
	v_pk_fma_f32 v[84:85], v[114:115], v[84:85], v[80:81] neg_lo:[1,0,0] neg_hi:[1,0,0]
	v_pk_fma_f32 v[80:81], v[174:175], s[40:41], v[146:147] op_sel_hi:[1,0,0]
	v_pk_mul_f32 v[114:115], v[170:171], s[50:51] op_sel_hi:[1,0]
	v_pk_fma_f32 v[80:81], v[174:175], v[80:81], s[44:45] op_sel_hi:[1,1,0]
	v_exp_f32_e32 v114, v114
	v_exp_f32_e32 v115, v115
	v_pk_fma_f32 v[80:81], v[174:175], v[80:81], s[46:47] op_sel_hi:[1,1,0]
	v_pk_fma_f32 v[80:81], v[174:175], v[80:81], s[48:49] op_sel_hi:[1,1,0]
	v_max_f32_e32 v82, 0, v82
	v_pk_mul_f32 v[80:81], v[174:175], v[80:81]
	v_max_f32_e32 v83, 0, v83
	v_pk_mul_f32 v[80:81], v[114:115], v[80:81]
	s_nop 0
	v_pk_fma_f32 v[80:81], v[158:159], v[80:81], v[82:83] neg_lo:[1,0,0] neg_hi:[1,0,0]
	v_pk_mul_f32 v[82:83], v[90:91], v[154:155] op_sel:[0,1] op_sel_hi:[1,1]
	v_cvt_pk_bf16_f32 v170, v82, v83
	v_pk_mul_f32 v[82:83], v[86:87], v[154:155] op_sel:[0,1] op_sel_hi:[1,1]
	v_cvt_pk_bf16_f32 v171, v82, v83
	v_pk_mul_f32 v[82:83], v[84:85], v[154:155] op_sel:[0,1] op_sel_hi:[1,1]
	v_cvt_pk_bf16_f32 v172, v82, v83
	v_pk_mul_f32 v[82:83], v[80:81], v[154:155] op_sel:[0,1] op_sel_hi:[1,1]
	v_cvt_pk_bf16_f32 v173, v82, v83
	global_store_dwordx4 v[156:157], v[170:173], off offset:256
	global_load_dword v169, v[150:151], off offset:192
	v_or_b32_e32 v82, 48, v154
	v_and_b32_e32 v155, 0x7fffffff, v77
	v_and_b32_e32 v154, 0x7fffffff, v76
	v_pk_fma_f32 v[114:115], v[154:155], s[38:39], 1.0 op_sel_hi:[1,0,0]
	v_ashrrev_i32_e32 v83, 31, v82
	v_rcp_f32_e32 v156, v114
	v_rcp_f32_e32 v157, v115
	v_lshlrev_b64 v[82:83], 15, v[82:83]
	v_lshl_add_u64 v[82:83], s[22:23], 0, v[82:83]
	v_pk_mul_f32 v[158:159], v[76:77], v[76:77]
	v_lshl_add_u64 v[114:115], v[82:83], 0, v[152:153]
	v_and_b32_e32 v83, 0x7fffffff, v79
	v_and_b32_e32 v82, 0x7fffffff, v78
	v_pk_fma_f32 v[152:153], v[156:157], s[40:41], v[146:147] op_sel_hi:[1,0,0]
	v_pk_mul_f32 v[158:159], v[158:159], s[50:51] op_sel_hi:[1,0]
	v_pk_fma_f32 v[152:153], v[156:157], v[152:153], s[44:45] op_sel_hi:[1,1,0]
	v_exp_f32_e32 v158, v158
	v_exp_f32_e32 v159, v159
	v_pk_fma_f32 v[170:171], v[82:83], s[38:39], 1.0 op_sel_hi:[1,0,0]
	v_pk_fma_f32 v[152:153], v[156:157], v[152:153], s[46:47] op_sel_hi:[1,1,0]
	v_rcp_f32_e32 v170, v170
	v_rcp_f32_e32 v171, v171
	v_pk_fma_f32 v[152:153], v[156:157], v[152:153], s[48:49] op_sel_hi:[1,1,0]
	v_pk_mul_f32 v[152:153], v[156:157], v[152:153]
	v_pk_mul_f32 v[156:157], v[78:79], v[78:79]
	v_max_f32_e32 v76, 0, v76
	v_max_f32_e32 v77, 0, v77
	v_pk_mul_f32 v[152:153], v[158:159], v[152:153]
	v_pk_fma_f32 v[152:153], v[154:155], v[152:153], v[76:77] neg_lo:[1,0,0] neg_hi:[1,0,0]
	v_pk_fma_f32 v[76:77], v[170:171], s[40:41], v[146:147] op_sel_hi:[1,0,0]
	v_pk_mul_f32 v[154:155], v[156:157], s[50:51] op_sel_hi:[1,0]
	v_pk_fma_f32 v[76:77], v[170:171], v[76:77], s[44:45] op_sel_hi:[1,1,0]
	v_exp_f32_e32 v154, v154
	v_exp_f32_e32 v155, v155
	v_pk_fma_f32 v[76:77], v[170:171], v[76:77], s[46:47] op_sel_hi:[1,1,0]
	v_pk_fma_f32 v[76:77], v[170:171], v[76:77], s[48:49] op_sel_hi:[1,1,0]
	v_max_f32_e32 v78, 0, v78
	v_pk_mul_f32 v[76:77], v[170:171], v[76:77]
	v_max_f32_e32 v79, 0, v79
	v_pk_mul_f32 v[76:77], v[154:155], v[76:77]
	v_and_b32_e32 v155, 0x7fffffff, v73
	v_and_b32_e32 v154, 0x7fffffff, v72
	v_pk_fma_f32 v[156:157], v[154:155], s[38:39], 1.0 op_sel_hi:[1,0,0]
	v_pk_mul_f32 v[158:159], v[72:73], v[72:73]
	v_rcp_f32_e32 v156, v156
	v_rcp_f32_e32 v157, v157
	v_pk_fma_f32 v[78:79], v[82:83], v[76:77], v[78:79] neg_lo:[1,0,0] neg_hi:[1,0,0]
	v_and_b32_e32 v83, 0x7fffffff, v75
	v_and_b32_e32 v82, 0x7fffffff, v74
	v_pk_fma_f32 v[76:77], v[156:157], s[40:41], v[146:147] op_sel_hi:[1,0,0]
	v_pk_mul_f32 v[158:159], v[158:159], s[50:51] op_sel_hi:[1,0]
	v_pk_fma_f32 v[76:77], v[156:157], v[76:77], s[44:45] op_sel_hi:[1,1,0]
	v_exp_f32_e32 v158, v158
	v_exp_f32_e32 v159, v159
	v_pk_fma_f32 v[170:171], v[82:83], s[38:39], 1.0 op_sel_hi:[1,0,0]
	v_pk_fma_f32 v[76:77], v[156:157], v[76:77], s[46:47] op_sel_hi:[1,1,0]
	v_rcp_f32_e32 v170, v170
	v_rcp_f32_e32 v171, v171
	v_pk_fma_f32 v[76:77], v[156:157], v[76:77], s[48:49] op_sel_hi:[1,1,0]
	v_pk_mul_f32 v[76:77], v[156:157], v[76:77]
	v_pk_mul_f32 v[156:157], v[74:75], v[74:75]
	v_max_f32_e32 v72, 0, v72
	v_max_f32_e32 v73, 0, v73
	v_pk_mul_f32 v[76:77], v[158:159], v[76:77]
	v_pk_fma_f32 v[76:77], v[154:155], v[76:77], v[72:73] neg_lo:[1,0,0] neg_hi:[1,0,0]
	v_pk_fma_f32 v[72:73], v[170:171], s[40:41], v[146:147] op_sel_hi:[1,0,0]
	v_pk_mul_f32 v[154:155], v[156:157], s[50:51] op_sel_hi:[1,0]
	v_pk_fma_f32 v[72:73], v[170:171], v[72:73], s[44:45] op_sel_hi:[1,1,0]
	v_exp_f32_e32 v154, v154
	v_exp_f32_e32 v155, v155
	v_pk_fma_f32 v[72:73], v[170:171], v[72:73], s[46:47] op_sel_hi:[1,1,0]
	v_pk_fma_f32 v[72:73], v[170:171], v[72:73], s[48:49] op_sel_hi:[1,1,0]
	v_max_f32_e32 v74, 0, v74
	v_pk_mul_f32 v[72:73], v[170:171], v[72:73]
	v_max_f32_e32 v75, 0, v75
	v_pk_mul_f32 v[72:73], v[154:155], v[72:73]
	v_pk_mul_f32 v[156:157], v[68:69], v[68:69]
	v_pk_fma_f32 v[72:73], v[82:83], v[72:73], v[74:75] neg_lo:[1,0,0] neg_hi:[1,0,0]
	s_waitcnt vmcnt(0)
	v_pk_mul_f32 v[74:75], v[152:153], v[168:169] op_sel:[0,1] op_sel_hi:[1,1]
	v_pk_fma_f32 v[82:83], v[152:153], v[152:153], v[98:99]
	v_cvt_pk_bf16_f32 v152, v74, v75
	v_pk_mul_f32 v[74:75], v[78:79], v[168:169] op_sel:[0,1] op_sel_hi:[1,1]
	v_cvt_pk_bf16_f32 v153, v74, v75
	v_pk_mul_f32 v[74:75], v[76:77], v[168:169] op_sel:[0,1] op_sel_hi:[1,1]
	v_cvt_pk_bf16_f32 v154, v74, v75
	v_pk_mul_f32 v[74:75], v[72:73], v[168:169] op_sel:[0,1] op_sel_hi:[1,1]
	v_cvt_pk_bf16_f32 v155, v74, v75
	v_and_b32_e32 v75, 0x7fffffff, v69
	v_and_b32_e32 v74, 0x7fffffff, v68
	v_pk_fma_f32 v[98:99], v[74:75], s[38:39], 1.0 op_sel_hi:[1,0,0]
	global_store_dwordx4 v[114:115], v[152:155], off
	v_rcp_f32_e32 v98, v98
	v_rcp_f32_e32 v99, v99
	v_and_b32_e32 v153, 0x7fffffff, v71
	v_and_b32_e32 v152, 0x7fffffff, v70
	v_pk_mul_f32 v[156:157], v[156:157], s[50:51] op_sel_hi:[1,0]
	v_pk_fma_f32 v[154:155], v[98:99], s[40:41], v[146:147] op_sel_hi:[1,0,0]
	v_exp_f32_e32 v156, v156
	v_pk_fma_f32 v[154:155], v[98:99], v[154:155], s[44:45] op_sel_hi:[1,1,0]
	v_exp_f32_e32 v157, v157
	v_pk_fma_f32 v[158:159], v[152:153], s[38:39], 1.0 op_sel_hi:[1,0,0]
	v_pk_fma_f32 v[154:155], v[98:99], v[154:155], s[46:47] op_sel_hi:[1,1,0]
	v_rcp_f32_e32 v158, v158
	v_rcp_f32_e32 v159, v159
	v_pk_fma_f32 v[154:155], v[98:99], v[154:155], s[48:49] op_sel_hi:[1,1,0]
	v_pk_mul_f32 v[98:99], v[98:99], v[154:155]
	v_pk_mul_f32 v[154:155], v[70:71], v[70:71]
	v_max_f32_e32 v68, 0, v68
	v_max_f32_e32 v69, 0, v69
	v_pk_mul_f32 v[98:99], v[156:157], v[98:99]
	v_pk_fma_f32 v[74:75], v[74:75], v[98:99], v[68:69] neg_lo:[1,0,0] neg_hi:[1,0,0]
	v_pk_fma_f32 v[68:69], v[158:159], s[40:41], v[146:147] op_sel_hi:[1,0,0]
	v_pk_mul_f32 v[98:99], v[154:155], s[50:51] op_sel_hi:[1,0]
	v_pk_fma_f32 v[68:69], v[158:159], v[68:69], s[44:45] op_sel_hi:[1,1,0]
	v_exp_f32_e32 v98, v98
	v_exp_f32_e32 v99, v99
	v_pk_fma_f32 v[68:69], v[158:159], v[68:69], s[46:47] op_sel_hi:[1,1,0]
	v_pk_fma_f32 v[68:69], v[158:159], v[68:69], s[48:49] op_sel_hi:[1,1,0]
	v_max_f32_e32 v70, 0, v70
	v_pk_mul_f32 v[68:69], v[158:159], v[68:69]
	v_max_f32_e32 v71, 0, v71
	v_pk_mul_f32 v[68:69], v[98:99], v[68:69]
	v_and_b32_e32 v99, 0x7fffffff, v65
	v_and_b32_e32 v98, 0x7fffffff, v64
	v_pk_fma_f32 v[154:155], v[98:99], s[38:39], 1.0 op_sel_hi:[1,0,0]
	v_pk_mul_f32 v[156:157], v[64:65], v[64:65]
	v_rcp_f32_e32 v154, v154
	v_rcp_f32_e32 v155, v155
	v_pk_fma_f32 v[70:71], v[152:153], v[68:69], v[70:71] neg_lo:[1,0,0] neg_hi:[1,0,0]
	v_and_b32_e32 v153, 0x7fffffff, v67
	v_and_b32_e32 v152, 0x7fffffff, v66
	v_pk_fma_f32 v[68:69], v[154:155], s[40:41], v[146:147] op_sel_hi:[1,0,0]
	v_pk_mul_f32 v[156:157], v[156:157], s[50:51] op_sel_hi:[1,0]
	v_pk_fma_f32 v[68:69], v[154:155], v[68:69], s[44:45] op_sel_hi:[1,1,0]
	v_exp_f32_e32 v156, v156
	v_exp_f32_e32 v157, v157
	v_pk_fma_f32 v[158:159], v[152:153], s[38:39], 1.0 op_sel_hi:[1,0,0]
	v_pk_fma_f32 v[68:69], v[154:155], v[68:69], s[46:47] op_sel_hi:[1,1,0]
	v_rcp_f32_e32 v158, v158
	v_rcp_f32_e32 v159, v159
	v_pk_fma_f32 v[68:69], v[154:155], v[68:69], s[48:49] op_sel_hi:[1,1,0]
	v_pk_mul_f32 v[68:69], v[154:155], v[68:69]
	v_pk_mul_f32 v[154:155], v[66:67], v[66:67]
	v_max_f32_e32 v64, 0, v64
	v_max_f32_e32 v65, 0, v65
	v_pk_mul_f32 v[68:69], v[156:157], v[68:69]
	v_pk_fma_f32 v[68:69], v[98:99], v[68:69], v[64:65] neg_lo:[1,0,0] neg_hi:[1,0,0]
	v_pk_fma_f32 v[64:65], v[158:159], s[40:41], v[146:147] op_sel_hi:[1,0,0]
	v_pk_mul_f32 v[98:99], v[154:155], s[50:51] op_sel_hi:[1,0]
	v_pk_fma_f32 v[64:65], v[158:159], v[64:65], s[44:45] op_sel_hi:[1,1,0]
	v_exp_f32_e32 v98, v98
	v_exp_f32_e32 v99, v99
	v_pk_fma_f32 v[64:65], v[158:159], v[64:65], s[46:47] op_sel_hi:[1,1,0]
	v_pk_fma_f32 v[64:65], v[158:159], v[64:65], s[48:49] op_sel_hi:[1,1,0]
	v_max_f32_e32 v66, 0, v66
	v_pk_mul_f32 v[64:65], v[158:159], v[64:65]
	v_max_f32_e32 v67, 0, v67
	v_pk_mul_f32 v[64:65], v[98:99], v[64:65]
	v_pk_mul_f32 v[156:157], v[60:61], v[60:61]
	v_pk_fma_f32 v[64:65], v[152:153], v[64:65], v[66:67] neg_lo:[1,0,0] neg_hi:[1,0,0]
	v_pk_mul_f32 v[66:67], v[74:75], v[168:169] op_sel:[0,1] op_sel_hi:[1,1]
	v_cvt_pk_bf16_f32 v152, v66, v67
	v_pk_mul_f32 v[66:67], v[70:71], v[168:169] op_sel:[0,1] op_sel_hi:[1,1]
	v_cvt_pk_bf16_f32 v153, v66, v67
	v_pk_mul_f32 v[66:67], v[68:69], v[168:169] op_sel:[0,1] op_sel_hi:[1,1]
	v_cvt_pk_bf16_f32 v154, v66, v67
	v_pk_mul_f32 v[66:67], v[64:65], v[168:169] op_sel:[0,1] op_sel_hi:[1,1]
	v_cvt_pk_bf16_f32 v155, v66, v67
	global_store_dwordx4 v[114:115], v[152:155], off offset:256
	global_load_dword v169, v[150:151], off offset:512
	v_and_b32_e32 v67, 0x7fffffff, v61
	v_and_b32_e32 v66, 0x7fffffff, v60
	v_pk_fma_f32 v[98:99], v[66:67], s[38:39], 1.0 op_sel_hi:[1,0,0]
	v_and_b32_e32 v153, 0x7fffffff, v63
	v_rcp_f32_e32 v114, v98
	v_rcp_f32_e32 v115, v99
	v_and_b32_e32 v152, 0x7fffffff, v62
	v_pk_mul_f32 v[156:157], v[156:157], s[50:51] op_sel_hi:[1,0]
	v_pk_fma_f32 v[158:159], v[152:153], s[38:39], 1.0 op_sel_hi:[1,0,0]
	v_pk_fma_f32 v[154:155], v[114:115], s[40:41], v[146:147] op_sel_hi:[1,0,0]
	v_exp_f32_e32 v156, v156
	v_pk_fma_f32 v[154:155], v[114:115], v[154:155], s[44:45] op_sel_hi:[1,1,0]
	v_exp_f32_e32 v157, v157
	v_pk_fma_f32 v[154:155], v[114:115], v[154:155], s[46:47] op_sel_hi:[1,1,0]
	v_rcp_f32_e32 v158, v158
	v_rcp_f32_e32 v159, v159
	v_pk_fma_f32 v[154:155], v[114:115], v[154:155], s[48:49] op_sel_hi:[1,1,0]
	v_pk_mul_f32 v[114:115], v[114:115], v[154:155]
	v_pk_mul_f32 v[154:155], v[62:63], v[62:63]
	v_max_f32_e32 v60, 0, v60
	v_max_f32_e32 v61, 0, v61
	v_pk_mul_f32 v[114:115], v[156:157], v[114:115]
	v_pk_fma_f32 v[114:115], v[66:67], v[114:115], v[60:61] neg_lo:[1,0,0] neg_hi:[1,0,0]
	v_pk_fma_f32 v[60:61], v[158:159], s[40:41], v[146:147] op_sel_hi:[1,0,0]
	v_pk_mul_f32 v[66:67], v[154:155], s[50:51] op_sel_hi:[1,0]
	v_pk_fma_f32 v[60:61], v[158:159], v[60:61], s[44:45] op_sel_hi:[1,1,0]
	v_exp_f32_e32 v66, v66
	v_exp_f32_e32 v67, v67
	v_pk_fma_f32 v[60:61], v[158:159], v[60:61], s[46:47] op_sel_hi:[1,1,0]
	v_pk_fma_f32 v[60:61], v[158:159], v[60:61], s[48:49] op_sel_hi:[1,1,0]
	v_max_f32_e32 v62, 0, v62
	v_pk_mul_f32 v[60:61], v[158:159], v[60:61]
	v_max_f32_e32 v63, 0, v63
	v_pk_mul_f32 v[60:61], v[66:67], v[60:61]
	v_and_b32_e32 v67, 0x7fffffff, v57
	v_and_b32_e32 v66, 0x7fffffff, v56
	v_pk_fma_f32 v[154:155], v[66:67], s[38:39], 1.0 op_sel_hi:[1,0,0]
	v_pk_mul_f32 v[156:157], v[56:57], v[56:57]
	v_rcp_f32_e32 v154, v154
	v_rcp_f32_e32 v155, v155
	v_pk_fma_f32 v[62:63], v[152:153], v[60:61], v[62:63] neg_lo:[1,0,0] neg_hi:[1,0,0]
	v_and_b32_e32 v153, 0x7fffffff, v59
	v_and_b32_e32 v152, 0x7fffffff, v58
	v_pk_fma_f32 v[60:61], v[154:155], s[40:41], v[146:147] op_sel_hi:[1,0,0]
	v_pk_mul_f32 v[156:157], v[156:157], s[50:51] op_sel_hi:[1,0]
	v_pk_fma_f32 v[60:61], v[154:155], v[60:61], s[44:45] op_sel_hi:[1,1,0]
	v_exp_f32_e32 v156, v156
	v_exp_f32_e32 v157, v157
	v_pk_fma_f32 v[158:159], v[152:153], s[38:39], 1.0 op_sel_hi:[1,0,0]
	v_pk_fma_f32 v[60:61], v[154:155], v[60:61], s[46:47] op_sel_hi:[1,1,0]
	v_rcp_f32_e32 v158, v158
	v_rcp_f32_e32 v159, v159
	v_pk_fma_f32 v[60:61], v[154:155], v[60:61], s[48:49] op_sel_hi:[1,1,0]
	v_pk_mul_f32 v[60:61], v[154:155], v[60:61]
	v_pk_mul_f32 v[154:155], v[58:59], v[58:59]
	v_max_f32_e32 v56, 0, v56
	v_max_f32_e32 v57, 0, v57
	v_pk_mul_f32 v[60:61], v[156:157], v[60:61]
	v_pk_fma_f32 v[60:61], v[66:67], v[60:61], v[56:57] neg_lo:[1,0,0] neg_hi:[1,0,0]
	v_pk_fma_f32 v[56:57], v[158:159], s[40:41], v[146:147] op_sel_hi:[1,0,0]
	v_pk_mul_f32 v[66:67], v[154:155], s[50:51] op_sel_hi:[1,0]
	v_pk_fma_f32 v[56:57], v[158:159], v[56:57], s[44:45] op_sel_hi:[1,1,0]
	v_exp_f32_e32 v66, v66
	v_exp_f32_e32 v67, v67
	v_pk_fma_f32 v[56:57], v[158:159], v[56:57], s[46:47] op_sel_hi:[1,1,0]
	v_pk_fma_f32 v[56:57], v[158:159], v[56:57], s[48:49] op_sel_hi:[1,1,0]
	v_max_f32_e32 v58, 0, v58
	v_pk_mul_f32 v[56:57], v[158:159], v[56:57]
	v_max_f32_e32 v59, 0, v59
	v_pk_mul_f32 v[56:57], v[66:67], v[56:57]
	v_pk_fma_f32 v[66:67], v[114:115], v[114:115], v[82:83]
	v_pk_fma_f32 v[56:57], v[152:153], v[56:57], v[58:59] neg_lo:[1,0,0] neg_hi:[1,0,0]
	s_waitcnt vmcnt(0)
	v_pk_mul_f32 v[58:59], v[114:115], v[168:169] op_sel:[0,1] op_sel_hi:[1,1]
	v_cvt_pk_bf16_f32 v152, v58, v59
	v_and_b32_e32 v83, 0x7fffffff, v53
	v_and_b32_e32 v82, 0x7fffffff, v52
	v_pk_mul_f32 v[58:59], v[62:63], v[168:169] op_sel:[0,1] op_sel_hi:[1,1]
	v_cvt_pk_bf16_f32 v153, v58, v59
	v_pk_fma_f32 v[114:115], v[82:83], s[38:39], 1.0 op_sel_hi:[1,0,0]
	v_pk_mul_f32 v[58:59], v[60:61], v[168:169] op_sel:[0,1] op_sel_hi:[1,1]
	v_cvt_pk_bf16_f32 v154, v58, v59
	v_rcp_f32_e32 v114, v114
	v_rcp_f32_e32 v115, v115
	v_pk_mul_f32 v[58:59], v[56:57], v[168:169] op_sel:[0,1] op_sel_hi:[1,1]
	v_cvt_pk_bf16_f32 v155, v58, v59
	v_add_co_u32_e32 v58, vcc, s86, v148
	v_lshl_add_u64 v[98:99], v[148:149], 0, s[54:55]
	s_nop 0
	v_addc_co_u32_e32 v59, vcc, 0, v149, vcc
	global_store_dwordx4 v[58:59], v[152:155], off
	v_pk_fma_f32 v[58:59], v[114:115], s[40:41], v[146:147] op_sel_hi:[1,0,0]
	s_nop 0
	v_pk_mul_f32 v[154:155], v[52:53], v[52:53]
	v_and_b32_e32 v153, 0x7fffffff, v55
	v_and_b32_e32 v152, 0x7fffffff, v54
	v_pk_mul_f32 v[154:155], v[154:155], s[50:51] op_sel_hi:[1,0]
	v_pk_fma_f32 v[58:59], v[114:115], v[58:59], s[44:45] op_sel_hi:[1,1,0]
	v_exp_f32_e32 v154, v154
	v_exp_f32_e32 v155, v155
	v_pk_fma_f32 v[156:157], v[152:153], s[38:39], 1.0 op_sel_hi:[1,0,0]
	v_pk_fma_f32 v[58:59], v[114:115], v[58:59], s[46:47] op_sel_hi:[1,1,0]
	v_rcp_f32_e32 v156, v156
	v_rcp_f32_e32 v157, v157
	v_pk_fma_f32 v[58:59], v[114:115], v[58:59], s[48:49] op_sel_hi:[1,1,0]
	v_pk_mul_f32 v[58:59], v[114:115], v[58:59]
	v_pk_mul_f32 v[114:115], v[54:55], v[54:55]
	v_max_f32_e32 v52, 0, v52
	v_max_f32_e32 v53, 0, v53
	v_pk_mul_f32 v[58:59], v[154:155], v[58:59]
	v_pk_fma_f32 v[58:59], v[82:83], v[58:59], v[52:53] neg_lo:[1,0,0] neg_hi:[1,0,0]
	v_pk_fma_f32 v[52:53], v[156:157], s[40:41], v[146:147] op_sel_hi:[1,0,0]
	v_pk_mul_f32 v[82:83], v[114:115], s[50:51] op_sel_hi:[1,0]
	v_pk_fma_f32 v[52:53], v[156:157], v[52:53], s[44:45] op_sel_hi:[1,1,0]
	v_exp_f32_e32 v82, v82
	v_exp_f32_e32 v83, v83
	v_pk_fma_f32 v[52:53], v[156:157], v[52:53], s[46:47] op_sel_hi:[1,1,0]
	v_pk_fma_f32 v[52:53], v[156:157], v[52:53], s[48:49] op_sel_hi:[1,1,0]
	v_max_f32_e32 v54, 0, v54
	v_pk_mul_f32 v[52:53], v[156:157], v[52:53]
	v_max_f32_e32 v55, 0, v55
	v_pk_mul_f32 v[52:53], v[82:83], v[52:53]
	v_and_b32_e32 v83, 0x7fffffff, v49
	v_and_b32_e32 v82, 0x7fffffff, v48
	v_pk_fma_f32 v[114:115], v[82:83], s[38:39], 1.0 op_sel_hi:[1,0,0]
	v_pk_mul_f32 v[154:155], v[48:49], v[48:49]
	v_rcp_f32_e32 v114, v114
	v_rcp_f32_e32 v115, v115
	v_pk_fma_f32 v[54:55], v[152:153], v[52:53], v[54:55] neg_lo:[1,0,0] neg_hi:[1,0,0]
	v_and_b32_e32 v153, 0x7fffffff, v51
	v_and_b32_e32 v152, 0x7fffffff, v50
	v_pk_fma_f32 v[52:53], v[114:115], s[40:41], v[146:147] op_sel_hi:[1,0,0]
	v_pk_mul_f32 v[154:155], v[154:155], s[50:51] op_sel_hi:[1,0]
	v_pk_fma_f32 v[52:53], v[114:115], v[52:53], s[44:45] op_sel_hi:[1,1,0]
	v_exp_f32_e32 v154, v154
	v_exp_f32_e32 v155, v155
	v_pk_fma_f32 v[156:157], v[152:153], s[38:39], 1.0 op_sel_hi:[1,0,0]
	v_pk_fma_f32 v[52:53], v[114:115], v[52:53], s[46:47] op_sel_hi:[1,1,0]
	v_rcp_f32_e32 v156, v156
	v_rcp_f32_e32 v157, v157
	v_pk_fma_f32 v[52:53], v[114:115], v[52:53], s[48:49] op_sel_hi:[1,1,0]
	v_pk_mul_f32 v[52:53], v[114:115], v[52:53]
	v_pk_mul_f32 v[114:115], v[50:51], v[50:51]
	v_max_f32_e32 v48, 0, v48
	v_max_f32_e32 v49, 0, v49
	v_pk_mul_f32 v[52:53], v[154:155], v[52:53]
	v_pk_fma_f32 v[52:53], v[82:83], v[52:53], v[48:49] neg_lo:[1,0,0] neg_hi:[1,0,0]
	v_pk_fma_f32 v[48:49], v[156:157], s[40:41], v[146:147] op_sel_hi:[1,0,0]
	v_pk_mul_f32 v[82:83], v[114:115], s[50:51] op_sel_hi:[1,0]
	v_pk_fma_f32 v[48:49], v[156:157], v[48:49], s[44:45] op_sel_hi:[1,1,0]
	v_exp_f32_e32 v82, v82
	v_exp_f32_e32 v83, v83
	v_pk_fma_f32 v[48:49], v[156:157], v[48:49], s[46:47] op_sel_hi:[1,1,0]
	v_pk_fma_f32 v[48:49], v[156:157], v[48:49], s[48:49] op_sel_hi:[1,1,0]
	v_max_f32_e32 v50, 0, v50
	v_pk_mul_f32 v[48:49], v[156:157], v[48:49]
	v_max_f32_e32 v51, 0, v51
	v_pk_mul_f32 v[48:49], v[82:83], v[48:49]
	v_and_b32_e32 v115, 0x7fffffff, v47
	v_pk_fma_f32 v[48:49], v[152:153], v[48:49], v[50:51] neg_lo:[1,0,0] neg_hi:[1,0,0]
	v_pk_mul_f32 v[50:51], v[58:59], v[168:169] op_sel:[0,1] op_sel_hi:[1,1]
	v_cvt_pk_bf16_f32 v152, v50, v51
	v_pk_mul_f32 v[50:51], v[54:55], v[168:169] op_sel:[0,1] op_sel_hi:[1,1]
	v_cvt_pk_bf16_f32 v153, v50, v51
	v_pk_mul_f32 v[50:51], v[52:53], v[168:169] op_sel:[0,1] op_sel_hi:[1,1]
	v_cvt_pk_bf16_f32 v154, v50, v51
	v_pk_mul_f32 v[50:51], v[48:49], v[168:169] op_sel:[0,1] op_sel_hi:[1,1]
	v_cvt_pk_bf16_f32 v155, v50, v51
	global_store_dwordx4 v[98:99], v[152:155], off offset:256
	global_load_dword v158, v[150:151], off offset:576
	v_and_b32_e32 v51, 0x7fffffff, v45
	v_and_b32_e32 v50, 0x7fffffff, v44
	v_pk_fma_f32 v[82:83], v[50:51], s[38:39], 1.0 op_sel_hi:[1,0,0]
	v_pk_mul_f32 v[154:155], v[44:45], v[44:45]
	v_rcp_f32_e32 v98, v82
	v_rcp_f32_e32 v99, v83
	v_and_b32_e32 v114, 0x7fffffff, v46
	v_pk_mul_f32 v[154:155], v[154:155], s[50:51] op_sel_hi:[1,0]
	v_pk_fma_f32 v[156:157], v[114:115], s[38:39], 1.0 op_sel_hi:[1,0,0]
	v_pk_fma_f32 v[152:153], v[98:99], s[40:41], v[146:147] op_sel_hi:[1,0,0]
	v_exp_f32_e32 v154, v154
	v_pk_fma_f32 v[152:153], v[98:99], v[152:153], s[44:45] op_sel_hi:[1,1,0]
	v_exp_f32_e32 v155, v155
	v_pk_fma_f32 v[152:153], v[98:99], v[152:153], s[46:47] op_sel_hi:[1,1,0]
	v_rcp_f32_e32 v156, v156
	v_rcp_f32_e32 v157, v157
	v_pk_fma_f32 v[152:153], v[98:99], v[152:153], s[48:49] op_sel_hi:[1,1,0]
	v_pk_mul_f32 v[98:99], v[98:99], v[152:153]
	v_pk_mul_f32 v[152:153], v[46:47], v[46:47]
	v_max_f32_e32 v44, 0, v44
	v_max_f32_e32 v45, 0, v45
	v_pk_mul_f32 v[98:99], v[154:155], v[98:99]
	v_pk_fma_f32 v[98:99], v[50:51], v[98:99], v[44:45] neg_lo:[1,0,0] neg_hi:[1,0,0]
	v_pk_fma_f32 v[44:45], v[156:157], s[40:41], v[146:147] op_sel_hi:[1,0,0]
	v_pk_mul_f32 v[50:51], v[152:153], s[50:51] op_sel_hi:[1,0]
	v_pk_fma_f32 v[44:45], v[156:157], v[44:45], s[44:45] op_sel_hi:[1,1,0]
	v_exp_f32_e32 v50, v50
	v_exp_f32_e32 v51, v51
	v_pk_fma_f32 v[44:45], v[156:157], v[44:45], s[46:47] op_sel_hi:[1,1,0]
	v_pk_fma_f32 v[44:45], v[156:157], v[44:45], s[48:49] op_sel_hi:[1,1,0]
	v_max_f32_e32 v46, 0, v46
	v_pk_mul_f32 v[44:45], v[156:157], v[44:45]
	v_max_f32_e32 v47, 0, v47
	v_pk_mul_f32 v[44:45], v[50:51], v[44:45]
	v_and_b32_e32 v51, 0x7fffffff, v41
	v_and_b32_e32 v50, 0x7fffffff, v40
	v_pk_fma_f32 v[152:153], v[50:51], s[38:39], 1.0 op_sel_hi:[1,0,0]
	v_pk_mul_f32 v[154:155], v[40:41], v[40:41]
	v_rcp_f32_e32 v152, v152
	v_rcp_f32_e32 v153, v153
	v_pk_fma_f32 v[46:47], v[114:115], v[44:45], v[46:47] neg_lo:[1,0,0] neg_hi:[1,0,0]
	v_and_b32_e32 v115, 0x7fffffff, v43
	v_and_b32_e32 v114, 0x7fffffff, v42
	v_pk_fma_f32 v[44:45], v[152:153], s[40:41], v[146:147] op_sel_hi:[1,0,0]
	v_pk_mul_f32 v[154:155], v[154:155], s[50:51] op_sel_hi:[1,0]
	v_pk_fma_f32 v[44:45], v[152:153], v[44:45], s[44:45] op_sel_hi:[1,1,0]
	v_exp_f32_e32 v154, v154
	v_exp_f32_e32 v155, v155
	v_pk_fma_f32 v[156:157], v[114:115], s[38:39], 1.0 op_sel_hi:[1,0,0]
	v_pk_fma_f32 v[44:45], v[152:153], v[44:45], s[46:47] op_sel_hi:[1,1,0]
	v_rcp_f32_e32 v156, v156
	v_rcp_f32_e32 v157, v157
	v_pk_fma_f32 v[44:45], v[152:153], v[44:45], s[48:49] op_sel_hi:[1,1,0]
	v_pk_mul_f32 v[44:45], v[152:153], v[44:45]
	v_pk_mul_f32 v[152:153], v[42:43], v[42:43]
	v_max_f32_e32 v40, 0, v40
	v_max_f32_e32 v41, 0, v41
	v_pk_mul_f32 v[44:45], v[154:155], v[44:45]
	v_pk_fma_f32 v[44:45], v[50:51], v[44:45], v[40:41] neg_lo:[1,0,0] neg_hi:[1,0,0]
	v_pk_fma_f32 v[40:41], v[156:157], s[40:41], v[146:147] op_sel_hi:[1,0,0]
	v_pk_mul_f32 v[50:51], v[152:153], s[50:51] op_sel_hi:[1,0]
	v_pk_fma_f32 v[40:41], v[156:157], v[40:41], s[44:45] op_sel_hi:[1,1,0]
	v_exp_f32_e32 v50, v50
	v_exp_f32_e32 v51, v51
	v_pk_fma_f32 v[40:41], v[156:157], v[40:41], s[46:47] op_sel_hi:[1,1,0]
	v_pk_fma_f32 v[40:41], v[156:157], v[40:41], s[48:49] op_sel_hi:[1,1,0]
	v_max_f32_e32 v42, 0, v42
	v_pk_mul_f32 v[40:41], v[156:157], v[40:41]
	v_max_f32_e32 v43, 0, v43
	v_pk_mul_f32 v[40:41], v[50:51], v[40:41]
	v_pk_fma_f32 v[50:51], v[98:99], v[98:99], v[66:67]
	v_pk_fma_f32 v[40:41], v[114:115], v[40:41], v[42:43] neg_lo:[1,0,0] neg_hi:[1,0,0]
	s_waitcnt vmcnt(0)
	v_pk_mul_f32 v[42:43], v[98:99], v[158:159] op_sel_hi:[1,0]
	v_cvt_pk_bf16_f32 v152, v42, v43
	v_and_b32_e32 v67, 0x7fffffff, v37
	v_and_b32_e32 v66, 0x7fffffff, v36
	v_pk_mul_f32 v[42:43], v[46:47], v[158:159] op_sel_hi:[1,0]
	v_cvt_pk_bf16_f32 v153, v42, v43
	v_pk_fma_f32 v[98:99], v[66:67], s[38:39], 1.0 op_sel_hi:[1,0,0]
	v_pk_mul_f32 v[42:43], v[44:45], v[158:159] op_sel_hi:[1,0]
	v_cvt_pk_bf16_f32 v154, v42, v43
	v_rcp_f32_e32 v98, v98
	v_rcp_f32_e32 v99, v99
	v_pk_mul_f32 v[42:43], v[40:41], v[158:159] op_sel_hi:[1,0]
	v_cvt_pk_bf16_f32 v155, v42, v43
	v_add_co_u32_e32 v42, vcc, s87, v148
	v_and_b32_e32 v115, 0x7fffffff, v39
	s_nop 0
	v_addc_co_u32_e32 v43, vcc, 0, v149, vcc
	global_store_dwordx4 v[42:43], v[152:155], off
	v_and_b32_e32 v114, 0x7fffffff, v38
	v_pk_fma_f32 v[42:43], v[98:99], s[40:41], v[146:147] op_sel_hi:[1,0,0]
	v_pk_mul_f32 v[152:153], v[36:37], v[36:37]
	v_pk_fma_f32 v[42:43], v[98:99], v[42:43], s[44:45] op_sel_hi:[1,1,0]
	v_pk_mul_f32 v[152:153], v[152:153], s[50:51] op_sel_hi:[1,0]
	v_pk_fma_f32 v[154:155], v[114:115], s[38:39], 1.0 op_sel_hi:[1,0,0]
	v_exp_f32_e32 v152, v152
	v_exp_f32_e32 v153, v153
	v_pk_fma_f32 v[42:43], v[98:99], v[42:43], s[46:47] op_sel_hi:[1,1,0]
	v_rcp_f32_e32 v154, v154
	v_rcp_f32_e32 v155, v155
	v_pk_fma_f32 v[42:43], v[98:99], v[42:43], s[48:49] op_sel_hi:[1,1,0]
	v_pk_mul_f32 v[42:43], v[98:99], v[42:43]
	v_pk_mul_f32 v[98:99], v[38:39], v[38:39]
	v_max_f32_e32 v36, 0, v36
	v_max_f32_e32 v37, 0, v37
	v_pk_mul_f32 v[42:43], v[152:153], v[42:43]
	v_pk_fma_f32 v[42:43], v[66:67], v[42:43], v[36:37] neg_lo:[1,0,0] neg_hi:[1,0,0]
	v_pk_fma_f32 v[36:37], v[154:155], s[40:41], v[146:147] op_sel_hi:[1,0,0]
	v_pk_mul_f32 v[66:67], v[98:99], s[50:51] op_sel_hi:[1,0]
	v_pk_fma_f32 v[36:37], v[154:155], v[36:37], s[44:45] op_sel_hi:[1,1,0]
	v_exp_f32_e32 v66, v66
	v_exp_f32_e32 v67, v67
	v_pk_fma_f32 v[36:37], v[154:155], v[36:37], s[46:47] op_sel_hi:[1,1,0]
	v_pk_fma_f32 v[36:37], v[154:155], v[36:37], s[48:49] op_sel_hi:[1,1,0]
	v_max_f32_e32 v38, 0, v38
	v_pk_mul_f32 v[36:37], v[154:155], v[36:37]
	v_max_f32_e32 v39, 0, v39
	v_pk_mul_f32 v[36:37], v[66:67], v[36:37]
	v_and_b32_e32 v67, 0x7fffffff, v33
	v_and_b32_e32 v66, 0x7fffffff, v32
	v_pk_fma_f32 v[98:99], v[66:67], s[38:39], 1.0 op_sel_hi:[1,0,0]
	v_pk_mul_f32 v[152:153], v[32:33], v[32:33]
	v_rcp_f32_e32 v98, v98
	v_rcp_f32_e32 v99, v99
	v_pk_fma_f32 v[38:39], v[114:115], v[36:37], v[38:39] neg_lo:[1,0,0] neg_hi:[1,0,0]
	v_and_b32_e32 v115, 0x7fffffff, v35
	v_and_b32_e32 v114, 0x7fffffff, v34
	v_pk_fma_f32 v[36:37], v[98:99], s[40:41], v[146:147] op_sel_hi:[1,0,0]
	v_pk_mul_f32 v[152:153], v[152:153], s[50:51] op_sel_hi:[1,0]
	v_pk_fma_f32 v[36:37], v[98:99], v[36:37], s[44:45] op_sel_hi:[1,1,0]
	v_exp_f32_e32 v152, v152
	v_exp_f32_e32 v153, v153
	v_pk_fma_f32 v[154:155], v[114:115], s[38:39], 1.0 op_sel_hi:[1,0,0]
	v_pk_fma_f32 v[36:37], v[98:99], v[36:37], s[46:47] op_sel_hi:[1,1,0]
	v_rcp_f32_e32 v154, v154
	v_rcp_f32_e32 v155, v155
	v_pk_fma_f32 v[36:37], v[98:99], v[36:37], s[48:49] op_sel_hi:[1,1,0]
	v_pk_mul_f32 v[36:37], v[98:99], v[36:37]
	v_pk_mul_f32 v[98:99], v[34:35], v[34:35]
	v_max_f32_e32 v32, 0, v32
	v_max_f32_e32 v33, 0, v33
	v_pk_mul_f32 v[36:37], v[152:153], v[36:37]
	v_pk_fma_f32 v[36:37], v[66:67], v[36:37], v[32:33] neg_lo:[1,0,0] neg_hi:[1,0,0]
	v_pk_fma_f32 v[32:33], v[154:155], s[40:41], v[146:147] op_sel_hi:[1,0,0]
	v_pk_mul_f32 v[66:67], v[98:99], s[50:51] op_sel_hi:[1,0]
	v_pk_fma_f32 v[32:33], v[154:155], v[32:33], s[44:45] op_sel_hi:[1,1,0]
	v_exp_f32_e32 v66, v66
	v_exp_f32_e32 v67, v67
	v_pk_fma_f32 v[32:33], v[154:155], v[32:33], s[46:47] op_sel_hi:[1,1,0]
	v_pk_fma_f32 v[32:33], v[154:155], v[32:33], s[48:49] op_sel_hi:[1,1,0]
	v_max_f32_e32 v34, 0, v34
	v_pk_mul_f32 v[32:33], v[154:155], v[32:33]
	v_max_f32_e32 v35, 0, v35
	v_pk_mul_f32 v[32:33], v[66:67], v[32:33]
	v_lshl_add_u64 v[82:83], v[148:149], 0, s[56:57]
	v_pk_fma_f32 v[32:33], v[114:115], v[32:33], v[34:35] neg_lo:[1,0,0] neg_hi:[1,0,0]
	v_pk_mul_f32 v[34:35], v[42:43], v[158:159] op_sel_hi:[1,0]
	v_cvt_pk_bf16_f32 v152, v34, v35
	v_pk_mul_f32 v[34:35], v[38:39], v[158:159] op_sel_hi:[1,0]
	v_cvt_pk_bf16_f32 v153, v34, v35
	v_pk_mul_f32 v[34:35], v[36:37], v[158:159] op_sel_hi:[1,0]
	v_cvt_pk_bf16_f32 v154, v34, v35
	v_pk_mul_f32 v[34:35], v[32:33], v[158:159] op_sel_hi:[1,0]
	v_cvt_pk_bf16_f32 v155, v34, v35
	global_store_dwordx4 v[82:83], v[152:155], off offset:256
	global_load_dword v156, v[150:151], off offset:640
	v_and_b32_e32 v35, 0x7fffffff, v29
	v_and_b32_e32 v34, 0x7fffffff, v28
	v_pk_fma_f32 v[66:67], v[34:35], s[38:39], 1.0 op_sel_hi:[1,0,0]
	v_pk_mul_f32 v[152:153], v[28:29], v[28:29]
	v_rcp_f32_e32 v82, v66
	v_rcp_f32_e32 v83, v67
	v_and_b32_e32 v99, 0x7fffffff, v31
	v_and_b32_e32 v98, 0x7fffffff, v30
	v_pk_mul_f32 v[152:153], v[152:153], s[50:51] op_sel_hi:[1,0]
	v_pk_fma_f32 v[114:115], v[82:83], s[40:41], v[146:147] op_sel_hi:[1,0,0]
	v_exp_f32_e32 v152, v152
	v_pk_fma_f32 v[114:115], v[82:83], v[114:115], s[44:45] op_sel_hi:[1,1,0]
	v_exp_f32_e32 v153, v153
	v_pk_fma_f32 v[154:155], v[98:99], s[38:39], 1.0 op_sel_hi:[1,0,0]
	v_pk_fma_f32 v[114:115], v[82:83], v[114:115], s[46:47] op_sel_hi:[1,1,0]
	v_rcp_f32_e32 v154, v154
	v_rcp_f32_e32 v155, v155
	v_pk_fma_f32 v[114:115], v[82:83], v[114:115], s[48:49] op_sel_hi:[1,1,0]
	v_pk_mul_f32 v[82:83], v[82:83], v[114:115]
	v_pk_mul_f32 v[114:115], v[30:31], v[30:31]
	v_max_f32_e32 v28, 0, v28
	v_max_f32_e32 v29, 0, v29
	v_pk_mul_f32 v[82:83], v[152:153], v[82:83]
	v_pk_fma_f32 v[82:83], v[34:35], v[82:83], v[28:29] neg_lo:[1,0,0] neg_hi:[1,0,0]
	v_pk_fma_f32 v[28:29], v[154:155], s[40:41], v[146:147] op_sel_hi:[1,0,0]
	v_pk_mul_f32 v[34:35], v[114:115], s[50:51] op_sel_hi:[1,0]
	v_pk_fma_f32 v[28:29], v[154:155], v[28:29], s[44:45] op_sel_hi:[1,1,0]
	v_exp_f32_e32 v34, v34
	v_exp_f32_e32 v35, v35
	v_pk_fma_f32 v[28:29], v[154:155], v[28:29], s[46:47] op_sel_hi:[1,1,0]
	v_pk_fma_f32 v[28:29], v[154:155], v[28:29], s[48:49] op_sel_hi:[1,1,0]
	v_max_f32_e32 v30, 0, v30
	v_pk_mul_f32 v[28:29], v[154:155], v[28:29]
	v_max_f32_e32 v31, 0, v31
	v_pk_mul_f32 v[28:29], v[34:35], v[28:29]
	v_and_b32_e32 v35, 0x7fffffff, v25
	v_and_b32_e32 v34, 0x7fffffff, v24
	v_pk_fma_f32 v[114:115], v[34:35], s[38:39], 1.0 op_sel_hi:[1,0,0]
	v_pk_mul_f32 v[152:153], v[24:25], v[24:25]
	v_rcp_f32_e32 v114, v114
	v_rcp_f32_e32 v115, v115
	v_pk_fma_f32 v[30:31], v[98:99], v[28:29], v[30:31] neg_lo:[1,0,0] neg_hi:[1,0,0]
	v_and_b32_e32 v99, 0x7fffffff, v27
	v_and_b32_e32 v98, 0x7fffffff, v26
	v_pk_fma_f32 v[28:29], v[114:115], s[40:41], v[146:147] op_sel_hi:[1,0,0]
	v_pk_mul_f32 v[152:153], v[152:153], s[50:51] op_sel_hi:[1,0]
	v_pk_fma_f32 v[28:29], v[114:115], v[28:29], s[44:45] op_sel_hi:[1,1,0]
	v_exp_f32_e32 v152, v152
	v_exp_f32_e32 v153, v153
	v_pk_fma_f32 v[154:155], v[98:99], s[38:39], 1.0 op_sel_hi:[1,0,0]
	v_pk_fma_f32 v[28:29], v[114:115], v[28:29], s[46:47] op_sel_hi:[1,1,0]
	v_rcp_f32_e32 v154, v154
	v_rcp_f32_e32 v155, v155
	v_pk_fma_f32 v[28:29], v[114:115], v[28:29], s[48:49] op_sel_hi:[1,1,0]
	v_pk_mul_f32 v[28:29], v[114:115], v[28:29]
	v_pk_mul_f32 v[114:115], v[26:27], v[26:27]
	v_max_f32_e32 v24, 0, v24
	v_max_f32_e32 v25, 0, v25
	v_pk_mul_f32 v[28:29], v[152:153], v[28:29]
	v_pk_fma_f32 v[28:29], v[34:35], v[28:29], v[24:25] neg_lo:[1,0,0] neg_hi:[1,0,0]
	v_pk_fma_f32 v[24:25], v[154:155], s[40:41], v[146:147] op_sel_hi:[1,0,0]
	v_pk_mul_f32 v[34:35], v[114:115], s[50:51] op_sel_hi:[1,0]
	v_pk_fma_f32 v[24:25], v[154:155], v[24:25], s[44:45] op_sel_hi:[1,1,0]
	v_exp_f32_e32 v34, v34
	v_exp_f32_e32 v35, v35
	v_pk_fma_f32 v[24:25], v[154:155], v[24:25], s[46:47] op_sel_hi:[1,1,0]
	v_pk_fma_f32 v[24:25], v[154:155], v[24:25], s[48:49] op_sel_hi:[1,1,0]
	v_max_f32_e32 v26, 0, v26
	v_pk_mul_f32 v[24:25], v[154:155], v[24:25]
	v_max_f32_e32 v27, 0, v27
	v_pk_mul_f32 v[24:25], v[34:35], v[24:25]
	v_pk_fma_f32 v[34:35], v[82:83], v[82:83], v[50:51]
	v_pk_fma_f32 v[24:25], v[98:99], v[24:25], v[26:27] neg_lo:[1,0,0] neg_hi:[1,0,0]
	s_waitcnt vmcnt(0)
	v_and_b32_e32 v51, 0x7fffffff, v21
	v_and_b32_e32 v50, 0x7fffffff, v20
	v_pk_mul_f32 v[26:27], v[82:83], v[156:157] op_sel_hi:[1,0]
	v_cvt_pk_bf16_f32 v152, v26, v27
	v_pk_fma_f32 v[82:83], v[50:51], s[38:39], 1.0 op_sel_hi:[1,0,0]
	v_pk_mul_f32 v[26:27], v[30:31], v[156:157] op_sel_hi:[1,0]
	v_cvt_pk_bf16_f32 v153, v26, v27
	v_rcp_f32_e32 v82, v82
	v_rcp_f32_e32 v83, v83
	v_pk_mul_f32 v[26:27], v[28:29], v[156:157] op_sel_hi:[1,0]
	v_cvt_pk_bf16_f32 v154, v26, v27
	v_pk_mul_f32 v[26:27], v[24:25], v[156:157] op_sel_hi:[1,0]
	v_cvt_pk_bf16_f32 v155, v26, v27
	v_add_co_u32_e32 v26, vcc, s88, v148
	v_pk_mul_f32 v[114:115], v[20:21], v[20:21]
	s_nop 0
	v_addc_co_u32_e32 v27, vcc, 0, v149, vcc
	global_store_dwordx4 v[26:27], v[152:155], off
	v_and_b32_e32 v99, 0x7fffffff, v23
	v_and_b32_e32 v98, 0x7fffffff, v22
	v_pk_fma_f32 v[26:27], v[82:83], s[40:41], v[146:147] op_sel_hi:[1,0,0]
	v_pk_mul_f32 v[114:115], v[114:115], s[50:51] op_sel_hi:[1,0]
	v_pk_fma_f32 v[26:27], v[82:83], v[26:27], s[44:45] op_sel_hi:[1,1,0]
	v_exp_f32_e32 v114, v114
	v_exp_f32_e32 v115, v115
	v_pk_fma_f32 v[152:153], v[98:99], s[38:39], 1.0 op_sel_hi:[1,0,0]
	v_pk_fma_f32 v[26:27], v[82:83], v[26:27], s[46:47] op_sel_hi:[1,1,0]
	v_rcp_f32_e32 v152, v152
	v_rcp_f32_e32 v153, v153
	v_pk_fma_f32 v[26:27], v[82:83], v[26:27], s[48:49] op_sel_hi:[1,1,0]
	v_pk_mul_f32 v[26:27], v[82:83], v[26:27]
	v_pk_mul_f32 v[82:83], v[22:23], v[22:23]
	v_max_f32_e32 v20, 0, v20
	v_max_f32_e32 v21, 0, v21
	v_pk_mul_f32 v[26:27], v[114:115], v[26:27]
	v_pk_fma_f32 v[26:27], v[50:51], v[26:27], v[20:21] neg_lo:[1,0,0] neg_hi:[1,0,0]
	v_pk_fma_f32 v[20:21], v[152:153], s[40:41], v[146:147] op_sel_hi:[1,0,0]
	v_pk_mul_f32 v[50:51], v[82:83], s[50:51] op_sel_hi:[1,0]
	v_pk_fma_f32 v[20:21], v[152:153], v[20:21], s[44:45] op_sel_hi:[1,1,0]
	v_exp_f32_e32 v50, v50
	v_exp_f32_e32 v51, v51
	v_pk_fma_f32 v[20:21], v[152:153], v[20:21], s[46:47] op_sel_hi:[1,1,0]
	v_pk_fma_f32 v[20:21], v[152:153], v[20:21], s[48:49] op_sel_hi:[1,1,0]
	v_max_f32_e32 v22, 0, v22
	v_pk_mul_f32 v[20:21], v[152:153], v[20:21]
	v_max_f32_e32 v23, 0, v23
	v_pk_mul_f32 v[20:21], v[50:51], v[20:21]
	v_and_b32_e32 v51, 0x7fffffff, v17
	v_and_b32_e32 v50, 0x7fffffff, v16
	v_pk_fma_f32 v[82:83], v[50:51], s[38:39], 1.0 op_sel_hi:[1,0,0]
	v_pk_mul_f32 v[114:115], v[16:17], v[16:17]
	v_rcp_f32_e32 v82, v82
	v_rcp_f32_e32 v83, v83
	v_pk_fma_f32 v[22:23], v[98:99], v[20:21], v[22:23] neg_lo:[1,0,0] neg_hi:[1,0,0]
	v_and_b32_e32 v99, 0x7fffffff, v19
	v_and_b32_e32 v98, 0x7fffffff, v18
	v_pk_fma_f32 v[20:21], v[82:83], s[40:41], v[146:147] op_sel_hi:[1,0,0]
	v_pk_mul_f32 v[114:115], v[114:115], s[50:51] op_sel_hi:[1,0]
	v_pk_fma_f32 v[20:21], v[82:83], v[20:21], s[44:45] op_sel_hi:[1,1,0]
	v_exp_f32_e32 v114, v114
	v_exp_f32_e32 v115, v115
	v_pk_fma_f32 v[152:153], v[98:99], s[38:39], 1.0 op_sel_hi:[1,0,0]
	v_pk_fma_f32 v[20:21], v[82:83], v[20:21], s[46:47] op_sel_hi:[1,1,0]
	v_rcp_f32_e32 v152, v152
	v_rcp_f32_e32 v153, v153
	v_pk_fma_f32 v[20:21], v[82:83], v[20:21], s[48:49] op_sel_hi:[1,1,0]
	v_pk_mul_f32 v[20:21], v[82:83], v[20:21]
	v_pk_mul_f32 v[82:83], v[18:19], v[18:19]
	v_max_f32_e32 v16, 0, v16
	v_max_f32_e32 v17, 0, v17
	v_pk_mul_f32 v[20:21], v[114:115], v[20:21]
	v_pk_fma_f32 v[20:21], v[50:51], v[20:21], v[16:17] neg_lo:[1,0,0] neg_hi:[1,0,0]
	v_pk_fma_f32 v[16:17], v[152:153], s[40:41], v[146:147] op_sel_hi:[1,0,0]
	v_pk_mul_f32 v[50:51], v[82:83], s[50:51] op_sel_hi:[1,0]
	v_pk_fma_f32 v[16:17], v[152:153], v[16:17], s[44:45] op_sel_hi:[1,1,0]
	v_exp_f32_e32 v50, v50
	v_exp_f32_e32 v51, v51
	v_pk_fma_f32 v[16:17], v[152:153], v[16:17], s[46:47] op_sel_hi:[1,1,0]
	v_pk_fma_f32 v[16:17], v[152:153], v[16:17], s[48:49] op_sel_hi:[1,1,0]
	v_max_f32_e32 v18, 0, v18
	v_pk_mul_f32 v[16:17], v[152:153], v[16:17]
	v_max_f32_e32 v19, 0, v19
	v_pk_mul_f32 v[16:17], v[50:51], v[16:17]
	v_lshl_add_u64 v[66:67], v[148:149], 0, s[58:59]
	v_pk_fma_f32 v[16:17], v[98:99], v[16:17], v[18:19] neg_lo:[1,0,0] neg_hi:[1,0,0]
	v_pk_mul_f32 v[18:19], v[26:27], v[156:157] op_sel_hi:[1,0]
	v_cvt_pk_bf16_f32 v152, v18, v19
	v_pk_mul_f32 v[18:19], v[22:23], v[156:157] op_sel_hi:[1,0]
	v_cvt_pk_bf16_f32 v153, v18, v19
	v_pk_mul_f32 v[18:19], v[20:21], v[156:157] op_sel_hi:[1,0]
	v_cvt_pk_bf16_f32 v154, v18, v19
	v_pk_mul_f32 v[18:19], v[16:17], v[156:157] op_sel_hi:[1,0]
	v_cvt_pk_bf16_f32 v155, v18, v19
	global_store_dwordx4 v[66:67], v[152:155], off offset:256
	global_load_dword v154, v[150:151], off offset:704
	v_and_b32_e32 v51, 0x7fffffff, v13
	v_and_b32_e32 v50, 0x7fffffff, v12
	v_pk_fma_f32 v[18:19], v[50:51], s[38:39], 1.0 op_sel_hi:[1,0,0]
	v_pk_mul_f32 v[114:115], v[12:13], v[12:13]
	v_rcp_f32_e32 v66, v18
	v_rcp_f32_e32 v67, v19
	v_and_b32_e32 v83, 0x7fffffff, v15
	v_and_b32_e32 v82, 0x7fffffff, v14
	v_pk_mul_f32 v[114:115], v[114:115], s[50:51] op_sel_hi:[1,0]
	v_pk_fma_f32 v[98:99], v[66:67], s[40:41], v[146:147] op_sel_hi:[1,0,0]
	v_exp_f32_e32 v114, v114
	v_pk_fma_f32 v[98:99], v[66:67], v[98:99], s[44:45] op_sel_hi:[1,1,0]
	v_exp_f32_e32 v115, v115
	v_pk_fma_f32 v[150:151], v[82:83], s[38:39], 1.0 op_sel_hi:[1,0,0]
	v_pk_fma_f32 v[98:99], v[66:67], v[98:99], s[46:47] op_sel_hi:[1,1,0]
	v_rcp_f32_e32 v150, v150
	v_rcp_f32_e32 v151, v151
	v_pk_fma_f32 v[98:99], v[66:67], v[98:99], s[48:49] op_sel_hi:[1,1,0]
	v_pk_mul_f32 v[66:67], v[66:67], v[98:99]
	v_pk_mul_f32 v[98:99], v[14:15], v[14:15]
	v_max_f32_e32 v12, 0, v12
	v_max_f32_e32 v13, 0, v13
	v_pk_mul_f32 v[66:67], v[114:115], v[66:67]
	v_pk_fma_f32 v[50:51], v[50:51], v[66:67], v[12:13] neg_lo:[1,0,0] neg_hi:[1,0,0]
	v_pk_fma_f32 v[12:13], v[150:151], s[40:41], v[146:147] op_sel_hi:[1,0,0]
	v_pk_mul_f32 v[66:67], v[98:99], s[50:51] op_sel_hi:[1,0]
	v_pk_fma_f32 v[12:13], v[150:151], v[12:13], s[44:45] op_sel_hi:[1,1,0]
	v_exp_f32_e32 v66, v66
	v_exp_f32_e32 v67, v67
	v_pk_fma_f32 v[12:13], v[150:151], v[12:13], s[46:47] op_sel_hi:[1,1,0]
	v_pk_fma_f32 v[12:13], v[150:151], v[12:13], s[48:49] op_sel_hi:[1,1,0]
	v_max_f32_e32 v14, 0, v14
	v_pk_mul_f32 v[12:13], v[150:151], v[12:13]
	v_max_f32_e32 v15, 0, v15
	v_pk_mul_f32 v[12:13], v[66:67], v[12:13]
	v_and_b32_e32 v67, 0x7fffffff, v9
	v_and_b32_e32 v66, 0x7fffffff, v8
	v_pk_fma_f32 v[98:99], v[66:67], s[38:39], 1.0 op_sel_hi:[1,0,0]
	v_pk_mul_f32 v[114:115], v[8:9], v[8:9]
	v_rcp_f32_e32 v98, v98
	v_rcp_f32_e32 v99, v99
	v_pk_fma_f32 v[14:15], v[82:83], v[12:13], v[14:15] neg_lo:[1,0,0] neg_hi:[1,0,0]
	v_and_b32_e32 v83, 0x7fffffff, v11
	v_and_b32_e32 v82, 0x7fffffff, v10
	v_pk_fma_f32 v[12:13], v[98:99], s[40:41], v[146:147] op_sel_hi:[1,0,0]
	v_pk_mul_f32 v[114:115], v[114:115], s[50:51] op_sel_hi:[1,0]
	v_pk_fma_f32 v[12:13], v[98:99], v[12:13], s[44:45] op_sel_hi:[1,1,0]
	v_exp_f32_e32 v114, v114
	v_exp_f32_e32 v115, v115
	v_pk_fma_f32 v[150:151], v[82:83], s[38:39], 1.0 op_sel_hi:[1,0,0]
	v_pk_fma_f32 v[12:13], v[98:99], v[12:13], s[46:47] op_sel_hi:[1,1,0]
	v_rcp_f32_e32 v150, v150
	v_rcp_f32_e32 v151, v151
	v_pk_fma_f32 v[12:13], v[98:99], v[12:13], s[48:49] op_sel_hi:[1,1,0]
	v_pk_mul_f32 v[12:13], v[98:99], v[12:13]
	v_pk_mul_f32 v[98:99], v[10:11], v[10:11]
	v_max_f32_e32 v8, 0, v8
	v_max_f32_e32 v9, 0, v9
	v_pk_mul_f32 v[12:13], v[114:115], v[12:13]
	v_pk_fma_f32 v[12:13], v[66:67], v[12:13], v[8:9] neg_lo:[1,0,0] neg_hi:[1,0,0]
	v_pk_fma_f32 v[8:9], v[150:151], s[40:41], v[146:147] op_sel_hi:[1,0,0]
	v_pk_mul_f32 v[66:67], v[98:99], s[50:51] op_sel_hi:[1,0]
	v_pk_fma_f32 v[8:9], v[150:151], v[8:9], s[44:45] op_sel_hi:[1,1,0]
	v_exp_f32_e32 v66, v66
	v_exp_f32_e32 v67, v67
	v_pk_fma_f32 v[8:9], v[150:151], v[8:9], s[46:47] op_sel_hi:[1,1,0]
	v_pk_fma_f32 v[8:9], v[150:151], v[8:9], s[48:49] op_sel_hi:[1,1,0]
	v_max_f32_e32 v10, 0, v10
	v_pk_mul_f32 v[8:9], v[150:151], v[8:9]
	v_max_f32_e32 v11, 0, v11
	v_pk_mul_f32 v[8:9], v[66:67], v[8:9]
	v_pk_fma_f32 v[34:35], v[50:51], v[50:51], v[34:35]
	v_pk_fma_f32 v[8:9], v[82:83], v[8:9], v[10:11] neg_lo:[1,0,0] neg_hi:[1,0,0]
	s_waitcnt vmcnt(0)
	v_pk_mul_f32 v[10:11], v[50:51], v[154:155] op_sel_hi:[1,0]
	v_and_b32_e32 v51, 0x7fffffff, v5
	v_and_b32_e32 v50, 0x7fffffff, v4
	v_cvt_pk_bf16_f32 v150, v10, v11
	v_pk_fma_f32 v[66:67], v[50:51], s[38:39], 1.0 op_sel_hi:[1,0,0]
	v_pk_mul_f32 v[10:11], v[14:15], v[154:155] op_sel_hi:[1,0]
	v_cvt_pk_bf16_f32 v151, v10, v11
	v_rcp_f32_e32 v66, v66
	v_rcp_f32_e32 v67, v67
	v_pk_mul_f32 v[10:11], v[12:13], v[154:155] op_sel_hi:[1,0]
	v_cvt_pk_bf16_f32 v152, v10, v11
	v_pk_mul_f32 v[10:11], v[8:9], v[154:155] op_sel_hi:[1,0]
	v_cvt_pk_bf16_f32 v153, v10, v11
	v_add_co_u32_e32 v10, vcc, s89, v148
	v_pk_mul_f32 v[98:99], v[4:5], v[4:5]
	s_nop 0
	v_addc_co_u32_e32 v11, vcc, 0, v149, vcc
	global_store_dwordx4 v[10:11], v[150:153], off
	v_and_b32_e32 v83, 0x7fffffff, v7
	v_and_b32_e32 v82, 0x7fffffff, v6
	v_pk_fma_f32 v[10:11], v[66:67], s[40:41], v[146:147] op_sel_hi:[1,0,0]
	v_pk_mul_f32 v[98:99], v[98:99], s[50:51] op_sel_hi:[1,0]
	v_pk_fma_f32 v[10:11], v[66:67], v[10:11], s[44:45] op_sel_hi:[1,1,0]
	v_exp_f32_e32 v98, v98
	v_exp_f32_e32 v99, v99
	v_pk_fma_f32 v[114:115], v[82:83], s[38:39], 1.0 op_sel_hi:[1,0,0]
	v_pk_fma_f32 v[10:11], v[66:67], v[10:11], s[46:47] op_sel_hi:[1,1,0]
	v_rcp_f32_e32 v114, v114
	v_rcp_f32_e32 v115, v115
	v_pk_fma_f32 v[10:11], v[66:67], v[10:11], s[48:49] op_sel_hi:[1,1,0]
	v_pk_mul_f32 v[10:11], v[66:67], v[10:11]
	v_pk_mul_f32 v[66:67], v[6:7], v[6:7]
	v_max_f32_e32 v4, 0, v4
	v_max_f32_e32 v5, 0, v5
	v_pk_mul_f32 v[10:11], v[98:99], v[10:11]
	v_pk_fma_f32 v[10:11], v[50:51], v[10:11], v[4:5] neg_lo:[1,0,0] neg_hi:[1,0,0]
	v_pk_fma_f32 v[4:5], v[114:115], s[40:41], v[146:147] op_sel_hi:[1,0,0]
	v_pk_mul_f32 v[50:51], v[66:67], s[50:51] op_sel_hi:[1,0]
	v_pk_fma_f32 v[4:5], v[114:115], v[4:5], s[44:45] op_sel_hi:[1,1,0]
	v_exp_f32_e32 v50, v50
	v_exp_f32_e32 v51, v51
	v_pk_fma_f32 v[4:5], v[114:115], v[4:5], s[46:47] op_sel_hi:[1,1,0]
	v_pk_fma_f32 v[4:5], v[114:115], v[4:5], s[48:49] op_sel_hi:[1,1,0]
	v_max_f32_e32 v6, 0, v6
	v_pk_mul_f32 v[4:5], v[114:115], v[4:5]
	v_max_f32_e32 v7, 0, v7
	v_pk_mul_f32 v[4:5], v[50:51], v[4:5]
	v_and_b32_e32 v51, 0x7fffffff, v1
	v_and_b32_e32 v50, 0x7fffffff, v0
	v_pk_fma_f32 v[66:67], v[50:51], s[38:39], 1.0 op_sel_hi:[1,0,0]
	v_pk_mul_f32 v[98:99], v[0:1], v[0:1]
	v_rcp_f32_e32 v66, v66
	v_rcp_f32_e32 v67, v67
	v_pk_fma_f32 v[6:7], v[82:83], v[4:5], v[6:7] neg_lo:[1,0,0] neg_hi:[1,0,0]
	v_and_b32_e32 v83, 0x7fffffff, v3
	v_and_b32_e32 v82, 0x7fffffff, v2
	v_pk_fma_f32 v[4:5], v[66:67], s[40:41], v[146:147] op_sel_hi:[1,0,0]
	v_pk_mul_f32 v[98:99], v[98:99], s[50:51] op_sel_hi:[1,0]
	v_pk_fma_f32 v[4:5], v[66:67], v[4:5], s[44:45] op_sel_hi:[1,1,0]
	v_exp_f32_e32 v98, v98
	v_exp_f32_e32 v99, v99
	v_pk_fma_f32 v[114:115], v[82:83], s[38:39], 1.0 op_sel_hi:[1,0,0]
	v_pk_fma_f32 v[4:5], v[66:67], v[4:5], s[46:47] op_sel_hi:[1,1,0]
	v_rcp_f32_e32 v114, v114
	v_rcp_f32_e32 v115, v115
	v_pk_fma_f32 v[4:5], v[66:67], v[4:5], s[48:49] op_sel_hi:[1,1,0]
	v_pk_mul_f32 v[4:5], v[66:67], v[4:5]
	v_pk_mul_f32 v[66:67], v[2:3], v[2:3]
	v_max_f32_e32 v0, 0, v0
	v_max_f32_e32 v1, 0, v1
	v_pk_mul_f32 v[4:5], v[98:99], v[4:5]
	v_pk_fma_f32 v[4:5], v[50:51], v[4:5], v[0:1] neg_lo:[1,0,0] neg_hi:[1,0,0]
	v_pk_fma_f32 v[0:1], v[114:115], s[40:41], v[146:147] op_sel_hi:[1,0,0]
	v_pk_mul_f32 v[50:51], v[66:67], s[50:51] op_sel_hi:[1,0]
	v_pk_fma_f32 v[0:1], v[114:115], v[0:1], s[44:45] op_sel_hi:[1,1,0]
	v_exp_f32_e32 v50, v50
	v_exp_f32_e32 v51, v51
	v_pk_fma_f32 v[0:1], v[114:115], v[0:1], s[46:47] op_sel_hi:[1,1,0]
	v_pk_fma_f32 v[0:1], v[114:115], v[0:1], s[48:49] op_sel_hi:[1,1,0]
	v_max_f32_e32 v2, 0, v2
	v_pk_mul_f32 v[0:1], v[114:115], v[0:1]
	v_max_f32_e32 v3, 0, v3
	v_pk_mul_f32 v[0:1], v[50:51], v[0:1]
	v_lshl_add_u64 v[18:19], v[148:149], 0, s[60:61]
	v_pk_fma_f32 v[2:3], v[82:83], v[0:1], v[2:3] neg_lo:[1,0,0] neg_hi:[1,0,0]
	v_pk_mul_f32 v[0:1], v[10:11], v[154:155] op_sel_hi:[1,0]
	v_cvt_pk_bf16_f32 v146, v0, v1
	v_pk_mul_f32 v[0:1], v[6:7], v[154:155] op_sel_hi:[1,0]
	v_cvt_pk_bf16_f32 v147, v0, v1
	v_pk_mul_f32 v[0:1], v[4:5], v[154:155] op_sel_hi:[1,0]
	v_cvt_pk_bf16_f32 v148, v0, v1
	v_pk_mul_f32 v[0:1], v[2:3], v[154:155] op_sel_hi:[1,0]
	v_cvt_pk_bf16_f32 v149, v0, v1
	global_store_dwordx4 v[18:19], v[146:149], off offset:256
	v_mov_b32_dpp v0, v34 row_ror:8 row_mask:0xf bank_mask:0xf
	v_add_f32_e32 v0, v34, v0
	s_nop 1
	v_mov_b32_dpp v1, v0 row_ror:4 row_mask:0xf bank_mask:0xf
	v_add_f32_e32 v0, v0, v1
	s_nop 1
	v_mov_b32_dpp v1, v0 row_ror:2 row_mask:0xf bank_mask:0xf
	v_add_f32_e32 v18, v0, v1
	v_lshl_add_u64 v[0:1], v[136:137], 3, s[16:17]
	s_nop 0
	v_mov_b32_dpp v19, v18 row_ror:1 row_mask:0xf bank_mask:0xf
	s_and_saveexec_b64 s[70:71], s[6:7]
	s_cbranch_execz .LBB0_283
	v_add_f32_e32 v18, v18, v19
	v_mul_f32_e32 v18, 0x4f800000, v18
	v_trunc_f32_e32 v18, v18
	v_mul_f32_e32 v19, 0x2f800000, v18
	v_floor_f32_e32 v19, v19
	v_fmac_f32_e32 v18, 0xcf800000, v19
	v_cvt_u32_f32_e32 v18, v18
	v_cvt_u32_f32_e32 v19, v19
	global_atomic_add_x2 v[0:1], v[18:19], off
